# flat2global stores: the 48 flat stores of the P3/P4 epilogues issued as global stores
# baseline (speedup 1.0000x reference)
; __device__ __forceinline__ unsigned cvtpk(float lo, float hi) { f32x2 v = {lo, hi}; bf16x2_t b = __builtin_convertvector(v, bf16x2_t); return __builtin_bit_cast(unsigned, b); }
;     __device__ __forceinline__ void operator()(const Acc& acc, const Unit& u, int wr, int wc, int fr, int fq) const {
;     ...
;         const int colbase = u.pn * 256 + wc * 64 + 8 * fq;
; #pragma unroll
;         for (int ai = 0; ai < 2; ++ai) {
;             f32x4 xv[4][2][2];
; #pragma unroll
;             for (int m = 0; m < 4; ++m) { const size_t off = (size_t)(u.pm * 256 + ai * 128 + wr * 64 + m * 16 + fr) * DM + colbase;
; #pragma unroll
;                 for (int bj = 0; bj < 2; ++bj) { xv[m][bj][0] = __builtin_nontemporal_load((const f32x4*)(x + off + 32 * bj)); xv[m][bj][1] = __builtin_nontemporal_load((const f32x4*)(x + off + 32 * bj + 4)); } }
; #pragma unroll
;             for (int m = 0; m < 4; ++m) {
;                 const int row = u.pm * 256 + ai * 128 + wr * 64 + m * 16 + fr;
;                 float ss = 0.f;
; #pragma unroll
;                 for (int bj = 0; bj < 2; ++bj) {
;                     const size_t off = (size_t)row * DM + colbase + 32 * bj;
;                     const f32x4 h0 = xv[m][bj][0] + acc[ai][bj][m][0], h1 = xv[m][bj][1] + acc[ai][bj][m][1];
;                     u32x4 w; w.x = cvtpk(h0.x, h0.y); w.y = cvtpk(h0.z, h0.w); w.z = cvtpk(h1.x, h1.y); w.w = cvtpk(h1.z, h1.w);
;                     *(u32x4*)(HB + off) = w;
;                     ss += (h0.x * h0.x + h0.y * h0.y) + (h0.z * h0.z + h0.w * h0.w) + (h1.x * h1.x + h1.y * h1.y) + (h1.z * h1.z + h1.w * h1.w);
;                 }
;                 ss = quad_sum(ss);
;                 if (fq == 0) atomicAdd(rowss + row, ss);
.LBB0_725:
	v_mov_b32_e32 v128, v200
	s_lshl_b32 s13, s22, 8
	s_or_b32 s13, s13, s86
	v_and_b32_e32 v129, 15, v128
	v_bfe_u32 v202, v128, 4, 2
	s_nop 0
	v_lshl_add_u32 v188, v202, 3, s13
	s_lshl_b32 s13, s20, 8
	s_add_i32 s13, s13, s79
	v_add_u32_e32 v192, s13, v129
	v_ashrrev_i32_e32 v189, 31, v188
	v_ashrrev_i32_e32 v193, 31, v192
	v_lshl_add_u64 v[190:191], v[188:189], 2, s[8:9]
	v_lshlrev_b64 v[128:129], 13, v[192:193]
	v_lshl_add_u64 v[128:129], v[190:191], 0, v[128:129]
	global_load_dwordx4 v[206:209], v[128:129], off nt
	global_load_dwordx4 v[210:213], v[128:129], off offset:16 nt
	global_load_dwordx4 v[214:217], v[128:129], off offset:128 nt
	global_load_dwordx4 v[218:221], v[128:129], off offset:144 nt
	v_add_u32_e32 v198, 16, v192
	v_add_u32_e32 v196, 32, v192
	v_add_u32_e32 v194, 48, v192
	v_ashrrev_i32_e32 v199, 31, v198
	v_ashrrev_i32_e32 v197, 31, v196
	v_ashrrev_i32_e32 v195, 31, v194
	v_lshlrev_b64 v[128:129], 13, v[198:199]
	v_lshlrev_b64 v[130:131], 13, v[196:197]
	v_lshlrev_b64 v[132:133], 13, v[194:195]
	v_lshl_add_u64 v[128:129], v[190:191], 0, v[128:129]
	v_lshl_add_u64 v[130:131], v[190:191], 0, v[130:131]
	v_lshl_add_u64 v[222:223], v[190:191], 0, v[132:133]
	global_load_dwordx4 v[172:175], v[128:129], off nt
	global_load_dwordx4 v[168:171], v[128:129], off offset:16 nt
	global_load_dwordx4 v[164:167], v[128:129], off offset:128 nt
	global_load_dwordx4 v[160:163], v[128:129], off offset:144 nt
	global_load_dwordx4 v[156:159], v[130:131], off nt
	global_load_dwordx4 v[152:155], v[130:131], off offset:16 nt
	global_load_dwordx4 v[148:151], v[130:131], off offset:128 nt
	global_load_dwordx4 v[144:147], v[130:131], off offset:144 nt
	global_load_dwordx4 v[140:143], v[222:223], off nt
	global_load_dwordx4 v[136:139], v[222:223], off offset:16 nt
	global_load_dwordx4 v[132:135], v[222:223], off offset:128 nt
	s_nop 0
	global_load_dwordx4 v[128:131], v[222:223], off offset:144 nt
	v_cmp_eq_u32_e32 vcc, 0, v202
	v_lshlrev_b64 v[222:223], 12, v[192:193]
	v_lshl_add_u64 v[222:223], s[10:11], 0, v[222:223]
	v_lshl_add_u64 v[222:223], v[188:189], 1, v[222:223]
	s_waitcnt vmcnt(0) lgkmcnt(0)
	v_pk_add_f32 v[126:127], v[126:127], v[208:209]
	v_pk_add_f32 v[124:125], v[124:125], v[206:207]
	v_pk_add_f32 v[118:119], v[118:119], v[216:217]
	v_pk_add_f32 v[206:207], v[116:117], v[214:215]
	v_pk_add_f32 v[120:121], v[120:121], v[210:211]
	v_pk_add_f32 v[210:211], v[112:113], v[218:219]
	v_cvt_pk_bf16_f32 v112, v124, v125
	v_cvt_pk_bf16_f32 v113, v126, v127
	v_mul_f32_e32 v125, v125, v125
	v_mul_f32_e32 v127, v127, v127
	v_cvt_pk_bf16_f32 v117, v118, v119
	v_mul_f32_e32 v202, v207, v207
	v_mul_f32_e32 v119, v119, v119
	v_pk_add_f32 v[122:123], v[122:123], v[212:213]
	v_pk_add_f32 v[208:209], v[114:115], v[220:221]
	v_cvt_pk_bf16_f32 v114, v120, v121
	v_mul_f32_e32 v121, v121, v121
	v_cvt_pk_bf16_f32 v116, v206, v207
	v_mul_f32_e32 v207, v211, v211
	v_fmac_f32_e32 v125, v124, v124
	v_fmac_f32_e32 v127, v126, v126
	v_fmac_f32_e32 v202, v206, v206
	v_fmac_f32_e32 v119, v118, v118
	v_cvt_pk_bf16_f32 v115, v122, v123
	v_mul_f32_e32 v123, v123, v123
	v_mul_f32_e32 v212, v209, v209
	v_fmac_f32_e32 v121, v120, v120
	v_fmac_f32_e32 v207, v210, v210
	v_add_f32_e32 v118, v125, v127
	v_add_f32_e32 v119, v202, v119
	v_fmac_f32_e32 v123, v122, v122
	v_fmac_f32_e32 v212, v208, v208
	v_add_f32_e32 v118, v118, v121
	v_add_f32_e32 v119, v119, v207
	v_add_f32_e32 v118, v123, v118
	v_add_f32_e32 v119, v212, v119
	v_add_f32_e32 v120, v118, v119
	ds_swizzle_b32 v121, v120 offset:swizzle(SWAP,16)
	v_cvt_pk_bf16_f32 v118, v210, v211
	v_cvt_pk_bf16_f32 v119, v208, v209
	v_mov_b64_e32 v[224:225], v[112:113]
	v_mov_b64_e32 v[226:227], v[114:115]
	global_store_dwordx4 v[222:223], v[112:115], off
	v_mov_b64_e32 v[214:215], v[116:117]
	v_mov_b64_e32 v[216:217], v[118:119]
	global_store_dwordx4 v[222:223], v[116:119], off offset:64
	s_waitcnt lgkmcnt(0)
	v_add_f32_e32 v114, v120, v121
	v_mov_b32_e32 v115, v114
	s_nop 1
	v_permlane32_swap_b32_e32 v114, v115
	v_lshl_add_u64 v[112:113], v[192:193], 2, s[6:7]
	s_and_saveexec_b64 s[20:21], vcc
	s_cbranch_execz .LBB0_727
	v_add_f32_e32 v114, v114, v115
	flat_atomic_add_f32 v[112:113], v114
.LBB0_727:
	s_or_b64 exec, exec, s[20:21]
	v_lshlrev_b64 v[114:115], 12, v[198:199]
	v_pk_add_f32 v[110:111], v[110:111], v[174:175]
	v_pk_add_f32 v[108:109], v[108:109], v[172:173]
	v_pk_add_f32 v[116:117], v[106:107], v[170:171]
	v_pk_add_f32 v[118:119], v[104:105], v[168:169]
	v_lshl_add_u64 v[114:115], s[10:11], 0, v[114:115]
	v_cvt_pk_bf16_f32 v104, v108, v109
	v_cvt_pk_bf16_f32 v105, v110, v111
	v_cvt_pk_bf16_f32 v106, v118, v119
	v_cvt_pk_bf16_f32 v107, v116, v117
	v_lshl_add_u64 v[114:115], v[188:189], 1, v[114:115]
	v_mov_b64_e32 v[228:229], v[104:105]
	v_mov_b64_e32 v[230:231], v[106:107]
	global_store_dwordx4 v[114:115], v[104:107], off
	v_pk_add_f32 v[100:101], v[100:101], v[164:165]
	v_pk_add_f32 v[102:103], v[102:103], v[166:167]
	v_mul_f32_e32 v104, v109, v109
	v_mul_f32_e32 v105, v111, v111
	v_fmac_f32_e32 v104, v108, v108
	v_fmac_f32_e32 v105, v110, v110
	v_add_f32_e32 v104, v104, v105
	v_mul_f32_e32 v105, v119, v119
	v_fmac_f32_e32 v105, v118, v118
	v_add_f32_e32 v104, v104, v105
	v_mul_f32_e32 v105, v117, v117
	v_fmac_f32_e32 v105, v116, v116
	v_add_f32_e32 v106, v105, v104
	v_pk_add_f32 v[104:105], v[98:99], v[162:163]
	v_pk_add_f32 v[98:99], v[96:97], v[160:161]
	v_mul_f32_e32 v97, v101, v101
	v_cvt_pk_bf16_f32 v96, v100, v101
	v_fmac_f32_e32 v97, v100, v100
	v_mul_f32_e32 v100, v103, v103
	v_fmac_f32_e32 v100, v102, v102
	v_add_f32_e32 v97, v97, v100
	v_mul_f32_e32 v100, v99, v99
	v_fmac_f32_e32 v100, v98, v98
	v_add_f32_e32 v97, v97, v100
	v_mul_f32_e32 v100, v105, v105
	v_fmac_f32_e32 v100, v104, v104
	v_add_f32_e32 v97, v100, v97
	v_add_f32_e32 v100, v106, v97
	ds_swizzle_b32 v101, v100 offset:swizzle(SWAP,16)
	v_cvt_pk_bf16_f32 v97, v102, v103
	v_cvt_pk_bf16_f32 v98, v98, v99
	v_cvt_pk_bf16_f32 v99, v104, v105
	v_mov_b64_e32 v[232:233], v[96:97]
	v_mov_b64_e32 v[234:235], v[98:99]
	global_store_dwordx4 v[114:115], v[96:99], off offset:64
	s_waitcnt lgkmcnt(0)
	s_nop 0
	v_add_f32_e32 v96, v100, v101
	v_mov_b32_e32 v97, v96
	s_nop 1
	v_permlane32_swap_b32_e32 v96, v97
	s_and_saveexec_b64 s[20:21], vcc
	s_cbranch_execz .LBB0_729
	v_add_f32_e32 v96, v96, v97
	flat_atomic_add_f32 v[112:113], v96 offset:64
; __device__ __forceinline__ unsigned cvtpk(float lo, float hi) { f32x2 v = {lo, hi}; bf16x2_t b = __builtin_convertvector(v, bf16x2_t); return __builtin_bit_cast(unsigned, b); }
;     __device__ __forceinline__ void operator()(const Acc& acc, const Unit& u, int wr, int wc, int fr, int fq) const {
;     ...
;             for (int m = 0; m < 4; ++m) {
;                 const int row = u.pm * 256 + ai * 128 + wr * 64 + m * 16 + fr;
;                 float ss = 0.f;
; #pragma unroll
;                 for (int bj = 0; bj < 2; ++bj) {
;                     const size_t off = (size_t)row * DM + colbase + 32 * bj;
;                     const f32x4 h0 = xv[m][bj][0] + acc[ai][bj][m][0], h1 = xv[m][bj][1] + acc[ai][bj][m][1];
;                     u32x4 w; w.x = cvtpk(h0.x, h0.y); w.y = cvtpk(h0.z, h0.w); w.z = cvtpk(h1.x, h1.y); w.w = cvtpk(h1.z, h1.w);
;                     *(u32x4*)(HB + off) = w;
;                     ss += (h0.x * h0.x + h0.y * h0.y) + (h0.z * h0.z + h0.w * h0.w) + (h1.x * h1.x + h1.y * h1.y) + (h1.z * h1.z + h1.w * h1.w);
;                 }
;                 ss = quad_sum(ss);
;                 if (fq == 0) atomicAdd(rowss + row, ss);
.LBB0_729:
	s_or_b64 exec, exec, s[20:21]
	v_lshlrev_b64 v[96:97], 12, v[196:197]
	v_pk_add_f32 v[94:95], v[94:95], v[158:159]
	v_pk_add_f32 v[92:93], v[92:93], v[156:157]
	v_pk_add_f32 v[98:99], v[90:91], v[154:155]
	v_pk_add_f32 v[100:101], v[88:89], v[152:153]
	v_lshl_add_u64 v[96:97], s[10:11], 0, v[96:97]
	v_cvt_pk_bf16_f32 v88, v92, v93
	v_cvt_pk_bf16_f32 v89, v94, v95
	v_cvt_pk_bf16_f32 v90, v100, v101
	v_cvt_pk_bf16_f32 v91, v98, v99
	v_lshl_add_u64 v[96:97], v[188:189], 1, v[96:97]
	v_mov_b64_e32 v[236:237], v[88:89]
	v_mov_b64_e32 v[238:239], v[90:91]
	global_store_dwordx4 v[96:97], v[88:91], off
	v_pk_add_f32 v[84:85], v[84:85], v[148:149]
	v_pk_add_f32 v[86:87], v[86:87], v[150:151]
	v_mul_f32_e32 v88, v93, v93
	v_mul_f32_e32 v89, v95, v95
	v_fmac_f32_e32 v88, v92, v92
	v_fmac_f32_e32 v89, v94, v94
	v_add_f32_e32 v88, v88, v89
	v_mul_f32_e32 v89, v101, v101
	v_fmac_f32_e32 v89, v100, v100
	v_add_f32_e32 v88, v88, v89
	v_mul_f32_e32 v89, v99, v99
	v_fmac_f32_e32 v89, v98, v98
	v_add_f32_e32 v90, v89, v88
	v_pk_add_f32 v[88:89], v[82:83], v[146:147]
	v_pk_add_f32 v[82:83], v[80:81], v[144:145]
	v_mul_f32_e32 v81, v85, v85
	v_cvt_pk_bf16_f32 v80, v84, v85
	v_fmac_f32_e32 v81, v84, v84
	v_mul_f32_e32 v84, v87, v87
	v_fmac_f32_e32 v84, v86, v86
	v_add_f32_e32 v81, v81, v84
	v_mul_f32_e32 v84, v83, v83
	v_fmac_f32_e32 v84, v82, v82
	v_add_f32_e32 v81, v81, v84
	v_mul_f32_e32 v84, v89, v89
	v_fmac_f32_e32 v84, v88, v88
	v_add_f32_e32 v81, v84, v81
	v_add_f32_e32 v84, v90, v81
	ds_swizzle_b32 v85, v84 offset:swizzle(SWAP,16)
	v_cvt_pk_bf16_f32 v81, v86, v87
	v_cvt_pk_bf16_f32 v82, v82, v83
	v_cvt_pk_bf16_f32 v83, v88, v89
	v_mov_b64_e32 v[240:241], v[80:81]
	v_mov_b64_e32 v[242:243], v[82:83]
	global_store_dwordx4 v[96:97], v[80:83], off offset:64
	s_waitcnt lgkmcnt(0)
	s_nop 0
	v_add_f32_e32 v80, v84, v85
	v_mov_b32_e32 v81, v80
	s_nop 1
	v_permlane32_swap_b32_e32 v80, v81
	s_and_saveexec_b64 s[20:21], vcc
	s_cbranch_execz .LBB0_731
	v_add_f32_e32 v80, v80, v81
	flat_atomic_add_f32 v[112:113], v80 offset:128
.LBB0_731:
	s_or_b64 exec, exec, s[20:21]
	v_lshlrev_b64 v[80:81], 12, v[194:195]
	v_pk_add_f32 v[78:79], v[78:79], v[142:143]
	v_pk_add_f32 v[76:77], v[76:77], v[140:141]
	v_pk_add_f32 v[82:83], v[74:75], v[138:139]
	v_pk_add_f32 v[84:85], v[72:73], v[136:137]
	v_lshl_add_u64 v[80:81], s[10:11], 0, v[80:81]
	v_cvt_pk_bf16_f32 v72, v76, v77
	v_cvt_pk_bf16_f32 v73, v78, v79
	v_cvt_pk_bf16_f32 v74, v84, v85
	v_cvt_pk_bf16_f32 v75, v82, v83
	v_lshl_add_u64 v[80:81], v[188:189], 1, v[80:81]
	v_mov_b64_e32 v[210:211], v[72:73]
	v_mov_b64_e32 v[212:213], v[74:75]
	global_store_dwordx4 v[80:81], v[72:75], off
	v_pk_add_f32 v[68:69], v[68:69], v[132:133]
	v_pk_add_f32 v[70:71], v[70:71], v[134:135]
	v_mul_f32_e32 v72, v77, v77
	v_mul_f32_e32 v73, v79, v79
	v_fmac_f32_e32 v72, v76, v76
	v_fmac_f32_e32 v73, v78, v78
	v_add_f32_e32 v72, v72, v73
	v_mul_f32_e32 v73, v85, v85
	v_fmac_f32_e32 v73, v84, v84
	v_add_f32_e32 v72, v72, v73
	v_mul_f32_e32 v73, v83, v83
	v_fmac_f32_e32 v73, v82, v82
	v_add_f32_e32 v74, v73, v72
	v_pk_add_f32 v[72:73], v[66:67], v[130:131]
	v_pk_add_f32 v[66:67], v[64:65], v[128:129]
	v_mul_f32_e32 v65, v69, v69
	v_cvt_pk_bf16_f32 v64, v68, v69
	v_fmac_f32_e32 v65, v68, v68
	v_mul_f32_e32 v68, v71, v71
	v_fmac_f32_e32 v68, v70, v70
	v_add_f32_e32 v65, v65, v68
	v_mul_f32_e32 v68, v67, v67
	v_fmac_f32_e32 v68, v66, v66
	v_add_f32_e32 v65, v65, v68
	v_mul_f32_e32 v68, v73, v73
	v_fmac_f32_e32 v68, v72, v72
	v_add_f32_e32 v65, v68, v65
	v_add_f32_e32 v68, v74, v65
	ds_swizzle_b32 v69, v68 offset:swizzle(SWAP,16)
	v_cvt_pk_bf16_f32 v65, v70, v71
	v_cvt_pk_bf16_f32 v66, v66, v67
	v_cvt_pk_bf16_f32 v67, v72, v73
	v_mov_b64_e32 v[244:245], v[64:65]
	v_mov_b64_e32 v[246:247], v[66:67]
	global_store_dwordx4 v[80:81], v[64:67], off offset:64
	s_waitcnt lgkmcnt(0)
	s_nop 0
	v_add_f32_e32 v64, v68, v69
	v_mov_b32_e32 v65, v64
	s_nop 1
	v_permlane32_swap_b32_e32 v64, v65
	s_and_saveexec_b64 s[20:21], vcc
	s_cbranch_execz .LBB0_733
	v_add_f32_e32 v64, v64, v65
	flat_atomic_add_f32 v[112:113], v64 offset:192
; __device__ __forceinline__ unsigned cvtpk(float lo, float hi) { f32x2 v = {lo, hi}; bf16x2_t b = __builtin_convertvector(v, bf16x2_t); return __builtin_bit_cast(unsigned, b); }
;     __device__ __forceinline__ void operator()(const Acc& acc, const Unit& u, int wr, int wc, int fr, int fq) const {
;     ...
;         for (int ai = 0; ai < 2; ++ai) {
;             f32x4 xv[4][2][2];
; #pragma unroll
;             for (int m = 0; m < 4; ++m) { const size_t off = (size_t)(u.pm * 256 + ai * 128 + wr * 64 + m * 16 + fr) * DM + colbase;
; #pragma unroll
;                 for (int bj = 0; bj < 2; ++bj) { xv[m][bj][0] = __builtin_nontemporal_load((const f32x4*)(x + off + 32 * bj)); xv[m][bj][1] = __builtin_nontemporal_load((const f32x4*)(x + off + 32 * bj + 4)); } }
; #pragma unroll
;             for (int m = 0; m < 4; ++m) {
;                 const int row = u.pm * 256 + ai * 128 + wr * 64 + m * 16 + fr;
;                 float ss = 0.f;
; #pragma unroll
;                 for (int bj = 0; bj < 2; ++bj) {
;                     const size_t off = (size_t)row * DM + colbase + 32 * bj;
;                     const f32x4 h0 = xv[m][bj][0] + acc[ai][bj][m][0], h1 = xv[m][bj][1] + acc[ai][bj][m][1];
;                     u32x4 w; w.x = cvtpk(h0.x, h0.y); w.y = cvtpk(h0.z, h0.w); w.z = cvtpk(h1.x, h1.y); w.w = cvtpk(h1.z, h1.w);
;                     *(u32x4*)(HB + off) = w;
;                     ss += (h0.x * h0.x + h0.y * h0.y) + (h0.z * h0.z + h0.w * h0.w) + (h1.x * h1.x + h1.y * h1.y) + (h1.z * h1.z + h1.w * h1.w);
;                 }
;                 ss = quad_sum(ss);
;                 if (fq == 0) atomicAdd(rowss + row, ss);
.LBB0_733:
	s_or_b64 exec, exec, s[20:21]
	v_add_u32_e32 v136, 0x80, v192
	v_ashrrev_i32_e32 v137, 31, v136
	v_lshlrev_b64 v[64:65], 13, v[136:137]
	v_lshl_add_u64 v[64:65], v[190:191], 0, v[64:65]
	global_load_dwordx4 v[120:123], v[64:65], off nt
	global_load_dwordx4 v[124:127], v[64:65], off offset:16 nt
	global_load_dwordx4 v[128:131], v[64:65], off offset:128 nt
	global_load_dwordx4 v[132:135], v[64:65], off offset:144 nt
	v_add_u32_e32 v118, 0x90, v192
	v_add_u32_e32 v116, 0xa0, v192
	v_add_u32_e32 v114, 0xb0, v192
	v_ashrrev_i32_e32 v119, 31, v118
	v_ashrrev_i32_e32 v117, 31, v116
	v_ashrrev_i32_e32 v115, 31, v114
	v_lshlrev_b64 v[64:65], 13, v[118:119]
	v_lshlrev_b64 v[66:67], 13, v[116:117]
	v_lshlrev_b64 v[68:69], 13, v[114:115]
	v_lshl_add_u64 v[64:65], v[190:191], 0, v[64:65]
	v_lshl_add_u64 v[66:67], v[190:191], 0, v[66:67]
	v_lshl_add_u64 v[138:139], v[190:191], 0, v[68:69]
	global_load_dwordx4 v[108:111], v[64:65], off nt
	global_load_dwordx4 v[104:107], v[64:65], off offset:16 nt
	global_load_dwordx4 v[100:103], v[64:65], off offset:128 nt
	global_load_dwordx4 v[96:99], v[64:65], off offset:144 nt
	global_load_dwordx4 v[92:95], v[66:67], off nt
	global_load_dwordx4 v[88:91], v[66:67], off offset:16 nt
	global_load_dwordx4 v[84:87], v[66:67], off offset:128 nt
	global_load_dwordx4 v[80:83], v[66:67], off offset:144 nt
	global_load_dwordx4 v[76:79], v[138:139], off nt
	global_load_dwordx4 v[72:75], v[138:139], off offset:16 nt
	global_load_dwordx4 v[68:71], v[138:139], off offset:128 nt
	s_nop 0
	global_load_dwordx4 v[64:67], v[138:139], off offset:144 nt
	v_lshlrev_b64 v[136:137], 12, v[136:137]
	v_lshl_add_u64 v[136:137], s[10:11], 0, v[136:137]
	v_lshl_add_u64 v[136:137], v[188:189], 1, v[136:137]
	s_waitcnt vmcnt(0) lgkmcnt(0)
	v_pk_add_f32 v[62:63], v[62:63], v[122:123]
	v_pk_add_f32 v[60:61], v[60:61], v[120:121]
	v_pk_add_f32 v[54:55], v[54:55], v[130:131]
	v_pk_add_f32 v[120:121], v[52:53], v[128:129]
	v_pk_add_f32 v[56:57], v[56:57], v[124:125]
	v_pk_add_f32 v[124:125], v[48:49], v[132:133]
	v_cvt_pk_bf16_f32 v48, v60, v61
	v_cvt_pk_bf16_f32 v49, v62, v63
	v_mul_f32_e32 v61, v61, v61
	v_mul_f32_e32 v63, v63, v63
	v_cvt_pk_bf16_f32 v52, v120, v121
	v_cvt_pk_bf16_f32 v53, v54, v55
	v_mul_f32_e32 v121, v121, v121
	v_mul_f32_e32 v55, v55, v55
	v_pk_add_f32 v[58:59], v[58:59], v[126:127]
	v_pk_add_f32 v[122:123], v[50:51], v[134:135]
	v_cvt_pk_bf16_f32 v50, v56, v57
	v_mul_f32_e32 v57, v57, v57
	v_mul_f32_e32 v126, v125, v125
	v_fmac_f32_e32 v61, v60, v60
	v_fmac_f32_e32 v63, v62, v62
	v_fmac_f32_e32 v121, v120, v120
	v_fmac_f32_e32 v55, v54, v54
	v_cvt_pk_bf16_f32 v51, v58, v59
	v_mul_f32_e32 v59, v59, v59
	v_mul_f32_e32 v127, v123, v123
	v_fmac_f32_e32 v57, v56, v56
	v_fmac_f32_e32 v126, v124, v124
	v_add_f32_e32 v54, v61, v63
	v_add_f32_e32 v55, v121, v55
	v_fmac_f32_e32 v59, v58, v58
	v_fmac_f32_e32 v127, v122, v122
	v_add_f32_e32 v54, v54, v57
	v_add_f32_e32 v55, v55, v126
	v_add_f32_e32 v54, v59, v54
	v_add_f32_e32 v55, v127, v55
	v_add_f32_e32 v56, v54, v55
	ds_swizzle_b32 v57, v56 offset:swizzle(SWAP,16)
	v_cvt_pk_bf16_f32 v54, v124, v125
	v_cvt_pk_bf16_f32 v55, v122, v123
	v_mov_b64_e32 v[248:249], v[48:49]
	v_mov_b64_e32 v[252:253], v[50:51]
	global_store_dwordx4 v[136:137], v[48:51], off
	v_mov_b64_e32 v[218:219], v[52:53]
	v_mov_b64_e32 v[220:221], v[54:55]
	global_store_dwordx4 v[136:137], v[52:55], off offset:64
	s_waitcnt lgkmcnt(0)
	v_add_f32_e32 v48, v56, v57
	v_mov_b32_e32 v49, v48
	s_nop 1
	v_permlane32_swap_b32_e32 v48, v49
	s_and_saveexec_b64 s[20:21], vcc
	s_cbranch_execz .LBB0_735
	v_add_f32_e32 v48, v48, v49
	flat_atomic_add_f32 v[112:113], v48 offset:512
.LBB0_735:
	s_or_b64 exec, exec, s[20:21]
	v_lshlrev_b64 v[48:49], 12, v[118:119]
	v_pk_add_f32 v[46:47], v[46:47], v[110:111]
	v_pk_add_f32 v[44:45], v[44:45], v[108:109]
	v_pk_add_f32 v[50:51], v[42:43], v[106:107]
	v_pk_add_f32 v[52:53], v[40:41], v[104:105]
	v_lshl_add_u64 v[48:49], s[10:11], 0, v[48:49]
	v_cvt_pk_bf16_f32 v40, v44, v45
	v_cvt_pk_bf16_f32 v41, v46, v47
	v_cvt_pk_bf16_f32 v42, v52, v53
	v_cvt_pk_bf16_f32 v43, v50, v51
	v_lshl_add_u64 v[48:49], v[188:189], 1, v[48:49]
	v_mov_b64_e32 v[222:223], v[40:41]
	v_mov_b64_e32 v[250:251], v[42:43]
	global_store_dwordx4 v[48:49], v[40:43], off
	v_pk_add_f32 v[36:37], v[36:37], v[100:101]
	v_pk_add_f32 v[38:39], v[38:39], v[102:103]
	v_mul_f32_e32 v40, v45, v45
	v_mul_f32_e32 v41, v47, v47
	v_fmac_f32_e32 v40, v44, v44
	v_fmac_f32_e32 v41, v46, v46
	v_add_f32_e32 v40, v40, v41
	v_mul_f32_e32 v41, v53, v53
	v_fmac_f32_e32 v41, v52, v52
	v_add_f32_e32 v40, v40, v41
	v_mul_f32_e32 v41, v51, v51
	v_fmac_f32_e32 v41, v50, v50
	v_add_f32_e32 v42, v41, v40
	v_pk_add_f32 v[40:41], v[34:35], v[98:99]
	v_pk_add_f32 v[34:35], v[32:33], v[96:97]
	v_mul_f32_e32 v33, v37, v37
	v_cvt_pk_bf16_f32 v32, v36, v37
	v_fmac_f32_e32 v33, v36, v36
	v_mul_f32_e32 v36, v39, v39
	v_fmac_f32_e32 v36, v38, v38
	v_add_f32_e32 v33, v33, v36
	v_mul_f32_e32 v36, v35, v35
	v_fmac_f32_e32 v36, v34, v34
	v_add_f32_e32 v33, v33, v36
	v_mul_f32_e32 v36, v41, v41
	v_fmac_f32_e32 v36, v40, v40
	v_add_f32_e32 v33, v36, v33
	v_add_f32_e32 v36, v42, v33
	ds_swizzle_b32 v37, v36 offset:swizzle(SWAP,16)
	v_cvt_pk_bf16_f32 v33, v38, v39
	v_cvt_pk_bf16_f32 v34, v34, v35
	v_cvt_pk_bf16_f32 v35, v40, v41
	v_mov_b32_e32 v206, 0x20000
	v_lshl_add_u32 v206, v200, 4, v206
	v_lshl_add_u32 v206, s79, 6, v206
	v_lshl_add_u32 v206, s86, 4, v206
	ds_write_b128 v206, v[32:35]
	global_store_dwordx4 v[48:49], v[32:35], off offset:64
	s_waitcnt lgkmcnt(0)
	s_nop 0
	v_add_f32_e32 v32, v36, v37
	v_mov_b32_e32 v33, v32
	s_nop 1
	v_permlane32_swap_b32_e32 v32, v33
	s_and_saveexec_b64 s[20:21], vcc
	s_cbranch_execz .LBB0_737
	v_add_f32_e32 v32, v32, v33
	flat_atomic_add_f32 v[112:113], v32 offset:576

; __device__ __forceinline__ unsigned cvtpk(float lo, float hi) { f32x2 v = {lo, hi}; bf16x2_t b = __builtin_convertvector(v, bf16x2_t); return __builtin_bit_cast(unsigned, b); }
;     __device__ __forceinline__ void operator()(const Acc& acc, const Unit& u, int wr, int wc, int fr, int fq) const {
;     ...
;             for (int m = 0; m < 4; ++m) {
;                 const int row = u.pm * 256 + ai * 128 + wr * 64 + m * 16 + fr;
;                 float ss = 0.f;
; #pragma unroll
;                 for (int bj = 0; bj < 2; ++bj) {
;                     const size_t off = (size_t)row * DM + colbase + 32 * bj;
;                     const f32x4 h0 = xv[m][bj][0] + acc[ai][bj][m][0], h1 = xv[m][bj][1] + acc[ai][bj][m][1];
;                     u32x4 w; w.x = cvtpk(h0.x, h0.y); w.y = cvtpk(h0.z, h0.w); w.z = cvtpk(h1.x, h1.y); w.w = cvtpk(h1.z, h1.w);
;                     *(u32x4*)(HB + off) = w;
;                     ss += (h0.x * h0.x + h0.y * h0.y) + (h0.z * h0.z + h0.w * h0.w) + (h1.x * h1.x + h1.y * h1.y) + (h1.z * h1.z + h1.w * h1.w);
;                 }
;                 ss = quad_sum(ss);
;                 if (fq == 0) atomicAdd(rowss + row, ss);
.Lhbk_ws:
	global_store_dwordx4 v[32:33], v[24:27], off
	v_pk_add_f32 v[20:21], v[20:21], v[84:85]
	v_pk_add_f32 v[22:23], v[22:23], v[86:87]
	v_mul_f32_e32 v24, v29, v29
	v_mul_f32_e32 v25, v31, v31
	v_fmac_f32_e32 v24, v28, v28
	v_fmac_f32_e32 v25, v30, v30
	v_add_f32_e32 v24, v24, v25
	v_mul_f32_e32 v25, v37, v37
	v_fmac_f32_e32 v25, v36, v36
	v_add_f32_e32 v24, v24, v25
	v_mul_f32_e32 v25, v35, v35
	v_fmac_f32_e32 v25, v34, v34
	v_add_f32_e32 v26, v25, v24
	v_pk_add_f32 v[24:25], v[18:19], v[82:83]
	v_pk_add_f32 v[18:19], v[16:17], v[80:81]
	v_mul_f32_e32 v17, v21, v21
	v_cvt_pk_bf16_f32 v16, v20, v21
	v_fmac_f32_e32 v17, v20, v20
	v_mul_f32_e32 v20, v23, v23
	v_fmac_f32_e32 v20, v22, v22
	v_add_f32_e32 v17, v17, v20
	v_mul_f32_e32 v20, v19, v19
	v_fmac_f32_e32 v20, v18, v18
	v_add_f32_e32 v17, v17, v20
	v_mul_f32_e32 v20, v25, v25
	v_fmac_f32_e32 v20, v24, v24
	v_add_f32_e32 v17, v20, v17
	v_add_f32_e32 v20, v26, v17
	ds_swizzle_b32 v21, v20 offset:swizzle(SWAP,16)
	v_cvt_pk_bf16_f32 v17, v22, v23
	v_cvt_pk_bf16_f32 v18, v18, v19
	v_cvt_pk_bf16_f32 v19, v24, v25
	global_store_dwordx4 v[32:33], v[16:19], off offset:64
	s_waitcnt lgkmcnt(0)
	s_nop 0
	v_add_f32_e32 v16, v20, v21
	v_mov_b32_e32 v17, v16
	s_nop 1
	v_permlane32_swap_b32_e32 v16, v17
	s_and_saveexec_b64 s[20:21], vcc
	s_cbranch_execz .LBB0_739
	v_add_f32_e32 v16, v16, v17
	flat_atomic_add_f32 v[112:113], v16 offset:640
.LBB0_739:
	s_or_b64 exec, exec, s[20:21]
	v_lshlrev_b64 v[16:17], 12, v[114:115]
	v_pk_add_f32 v[14:15], v[14:15], v[78:79]
	v_pk_add_f32 v[12:13], v[12:13], v[76:77]
	v_pk_add_f32 v[18:19], v[10:11], v[74:75]
	v_pk_add_f32 v[20:21], v[8:9], v[72:73]
	v_lshl_add_u64 v[16:17], s[10:11], 0, v[16:17]
	v_cvt_pk_bf16_f32 v8, v12, v13
	v_cvt_pk_bf16_f32 v9, v14, v15
	v_cvt_pk_bf16_f32 v10, v20, v21
	v_cvt_pk_bf16_f32 v11, v18, v19
	v_lshl_add_u64 v[16:17], v[188:189], 1, v[16:17]
	global_store_dwordx4 v[16:17], v[8:11], off
	v_pk_add_f32 v[4:5], v[4:5], v[68:69]
	v_pk_add_f32 v[6:7], v[6:7], v[70:71]
	v_mul_f32_e32 v8, v13, v13
	v_mul_f32_e32 v9, v15, v15
	v_fmac_f32_e32 v8, v12, v12
	v_fmac_f32_e32 v9, v14, v14
	v_add_f32_e32 v8, v8, v9
	v_mul_f32_e32 v9, v21, v21
	v_fmac_f32_e32 v9, v20, v20
	v_add_f32_e32 v8, v8, v9
	v_mul_f32_e32 v9, v19, v19
	v_fmac_f32_e32 v9, v18, v18
	v_add_f32_e32 v10, v9, v8
	v_pk_add_f32 v[8:9], v[2:3], v[66:67]
	v_pk_add_f32 v[2:3], v[0:1], v[64:65]
	v_mul_f32_e32 v1, v5, v5
	v_cvt_pk_bf16_f32 v0, v4, v5
	v_fmac_f32_e32 v1, v4, v4
	v_mul_f32_e32 v4, v7, v7
	v_fmac_f32_e32 v4, v6, v6
	v_add_f32_e32 v1, v1, v4
	v_mul_f32_e32 v4, v3, v3
	v_fmac_f32_e32 v4, v2, v2
	v_add_f32_e32 v1, v1, v4
	v_mul_f32_e32 v4, v9, v9
	v_fmac_f32_e32 v4, v8, v8
	v_add_f32_e32 v1, v4, v1
	v_add_f32_e32 v4, v10, v1
	ds_swizzle_b32 v5, v4 offset:swizzle(SWAP,16)
	v_cvt_pk_bf16_f32 v1, v6, v7
	v_cvt_pk_bf16_f32 v2, v2, v3
	v_cvt_pk_bf16_f32 v3, v8, v9
	global_store_dwordx4 v[16:17], v[0:3], off offset:64
	s_waitcnt lgkmcnt(0)
	s_nop 0
	v_add_f32_e32 v0, v4, v5
	v_mov_b32_e32 v1, v0
	s_nop 1
	v_permlane32_swap_b32_e32 v0, v1
	s_and_saveexec_b64 s[20:21], vcc
	s_cbranch_execz .LBB0_741
	v_add_f32_e32 v0, v0, v1
	flat_atomic_add_f32 v[112:113], v0 offset:704

;     __device__ __forceinline__ void operator()(const Acc& acc, const Unit& u, int wr, int wc, int fr, int fq) const {
;     ...
;         const int colbase = u.pn * 256 + wc * 64 + 8 * fq;
; #pragma unroll
;         for (int ai = 0; ai < 2; ++ai) {
;             f32x4 hv[4][2][2]; u32x4 pw[4][2]; float rsv[4];
; #pragma unroll
;             for (int m = 0; m < 4; ++m) { const int row = u.pm * 256 + ai * 128 + wr * 64 + m * 16 + fr; const size_t off = (size_t)row * DM + colbase;
;                 rsv[m] = rowss[row];
; #pragma unroll
;                 for (int bj = 0; bj < 2; ++bj) { const u32x4 hw = __builtin_nontemporal_load((const u32x4*)(hin + off + 32 * bj));
;                     hv[m][bj][0] = (f32x4){bflo(hw.x), bfhi(hw.x), bflo(hw.y), bfhi(hw.y)}; hv[m][bj][1] = (f32x4){bflo(hw.z), bfhi(hw.z), bflo(hw.w), bfhi(hw.w)};
;                     pw[m][bj] = __builtin_nontemporal_load((const u32x4*)(PP + off + 32 * bj)); } }
; #pragma unroll
;             for (int m = 0; m < 4; ++m) {
;                 const int row = u.pm * 256 + ai * 128 + wr * 64 + m * 16 + fr;
;                 const float rs = rsqrtf(rsv[m] * (1.0f / DM) + EPS) * -1.4426950408889634f;
; #pragma unroll
;                 for (int bj = 0; bj < 2; ++bj) {
;                     const size_t off = (size_t)row * DM + colbase + 32 * bj;
;                     f32x4 h0 = hv[m][bj][0], h1 = hv[m][bj][1];
;                     const u32x4 p4 = pw[m][bj];
;                     const f32x4 a0 = acc[ai][bj][m][0], a1 = acc[ai][bj][m][1];
;                     h0.x += bflo(p4.x) * __builtin_amdgcn_rcpf(1.0f + __builtin_amdgcn_exp2f(a0.x * rs));
;                     h0.y += bfhi(p4.x) * __builtin_amdgcn_rcpf(1.0f + __builtin_amdgcn_exp2f(a0.y * rs));
;                     h0.z += bflo(p4.y) * __builtin_amdgcn_rcpf(1.0f + __builtin_amdgcn_exp2f(a0.z * rs));
;                     h0.w += bfhi(p4.y) * __builtin_amdgcn_rcpf(1.0f + __builtin_amdgcn_exp2f(a0.w * rs));
;                     h1.x += bflo(p4.z) * __builtin_amdgcn_rcpf(1.0f + __builtin_amdgcn_exp2f(a1.x * rs));
;                     h1.y += bfhi(p4.z) * __builtin_amdgcn_rcpf(1.0f + __builtin_amdgcn_exp2f(a1.y * rs));
;                     h1.z += bflo(p4.w) * __builtin_amdgcn_rcpf(1.0f + __builtin_amdgcn_exp2f(a1.z * rs));
;                     h1.w += bfhi(p4.w) * __builtin_amdgcn_rcpf(1.0f + __builtin_amdgcn_exp2f(a1.w * rs));
.LBB0_814:
	v_mov_b64_e32 v[206:207], v[224:225]
	v_mov_b64_e32 v[208:209], v[226:227]
	v_mov_b64_e32 v[172:173], v[228:229]
	v_mov_b64_e32 v[174:175], v[230:231]
	v_mov_b64_e32 v[164:165], v[232:233]
	v_mov_b64_e32 v[166:167], v[234:235]
	v_mov_b64_e32 v[156:157], v[236:237]
	v_mov_b64_e32 v[158:159], v[238:239]
	v_mov_b64_e32 v[148:149], v[240:241]
	v_mov_b64_e32 v[150:151], v[242:243]
	v_mov_b64_e32 v[140:141], v[210:211]
	v_mov_b64_e32 v[142:143], v[212:213]
	v_mov_b64_e32 v[236:237], v[218:219]
	v_mov_b64_e32 v[238:239], v[220:221]
	v_mov_b64_e32 v[240:241], v[222:223]
	v_mov_b32_e32 v128, v200
	s_lshl_b32 s11, s42, 8
	v_and_b32_e32 v129, 15, v128
	v_bfe_u32 v128, v128, 4, 2
	s_or_b32 s11, s11, s86
	s_nop 0
	v_lshl_add_u32 v188, v128, 3, s11
	s_lshl_b32 s11, s41, 8
	s_add_i32 s11, s11, s79
	v_add_u32_e32 v190, s11, v129
	v_ashrrev_i32_e32 v191, 31, v190
	v_lshl_add_u64 v[192:193], v[190:191], 2, s[80:81]
	global_load_dword v226, v[192:193], off
	v_ashrrev_i32_e32 v189, 31, v188
	v_lshlrev_b64 v[128:129], 11, v[190:191]
	v_lshl_add_u64 v[222:223], v[128:129], 0, v[188:189]
	v_lshlrev_b64 v[128:129], 1, v[222:223]
	v_lshl_add_u64 v[130:131], s[6:7], 0, v[128:129]
	v_lshl_add_u64 v[128:129], s[8:9], 0, v[128:129]
	global_load_dwordx4 v[210:213], v[128:129], off nt
	global_load_dword v234, v[192:193], off offset:64
	global_load_dword v235, v[192:193], off offset:128
	global_load_dword v191, v[192:193], off offset:192
	global_load_dwordx4 v[218:221], v[128:129], off offset:64 nt
	v_add_u32_e32 v132, 16, v190
	v_add_u32_e32 v134, 32, v190
	v_add_u32_e32 v136, 48, v190
	v_ashrrev_i32_e32 v133, 31, v132
	v_ashrrev_i32_e32 v135, 31, v134
	v_ashrrev_i32_e32 v137, 31, v136
	v_lshlrev_b64 v[132:133], 11, v[132:133]
	v_lshlrev_b64 v[134:135], 11, v[134:135]
	v_lshlrev_b64 v[136:137], 11, v[136:137]
	v_lshl_add_u64 v[198:199], v[132:133], 0, v[188:189]
	v_lshl_add_u64 v[196:197], v[134:135], 0, v[188:189]
	v_lshl_add_u64 v[194:195], v[136:137], 0, v[188:189]
	v_lshlrev_b64 v[132:133], 1, v[198:199]
	v_lshlrev_b64 v[134:135], 1, v[196:197]
	v_lshlrev_b64 v[136:137], 1, v[194:195]
	v_lshl_add_u64 v[128:129], s[6:7], 0, v[132:133]
	v_lshl_add_u64 v[130:131], s[8:9], 0, v[132:133]
	v_lshl_add_u64 v[132:133], s[6:7], 0, v[134:135]
	v_lshl_add_u64 v[134:135], s[8:9], 0, v[134:135]
	v_lshl_add_u64 v[138:139], s[6:7], 0, v[136:137]
	v_lshl_add_u64 v[224:225], s[8:9], 0, v[136:137]
	global_load_dwordx4 v[168:171], v[130:131], off nt
	global_load_dwordx4 v[160:163], v[130:131], off offset:64 nt
	global_load_dwordx4 v[152:155], v[134:135], off nt
	global_load_dwordx4 v[144:147], v[134:135], off offset:64 nt
	s_nop 0
	v_mov_b64_e32 v[132:133], v[244:245]
	v_mov_b64_e32 v[134:135], v[246:247]
	s_nop 0
	global_load_dwordx4 v[136:139], v[224:225], off nt
	global_load_dwordx4 v[128:131], v[224:225], off offset:64 nt
	s_waitcnt vmcnt(0) lgkmcnt(0)
	v_fmamk_f32 v224, v226, 0x3a000000, v205
	v_mul_f32_e32 v225, 0x4b800000, v224
	v_cmp_gt_f32_e32 vcc, s40, v224
	v_lshlrev_b32_e32 v228, 16, v208
	s_nop 0
	v_cndmask_b32_e32 v224, v224, v225, vcc
	v_rsq_f32_e32 v232, v224
	v_and_b32_e32 v229, 0xffff0000, v208
	v_lshlrev_b32_e32 v230, 16, v212
	v_and_b32_e32 v231, 0xffff0000, v212
	v_mul_f32_e32 v208, 0x45800000, v232
	v_cndmask_b32_e32 v208, v232, v208, vcc
	v_mul_f32_e32 v212, 0xbfb8aa3b, v208
	v_mul_f32_e32 v124, v124, v212
	v_mul_f32_e32 v125, v125, v212
	v_mul_f32_e32 v120, v120, v212
	v_mul_f32_e32 v121, v121, v212
	v_exp_f32_e32 v124, v124
	v_exp_f32_e32 v125, v125
	v_exp_f32_e32 v120, v120
	v_exp_f32_e32 v121, v121
	v_add_f32_e32 v124, 1.0, v124
	v_add_f32_e32 v125, 1.0, v125
	v_add_f32_e32 v208, 1.0, v120
	v_add_f32_e32 v233, 1.0, v121
	v_rcp_f32_e32 v120, v124
	v_rcp_f32_e32 v121, v125
	v_lshlrev_b32_e32 v224, 16, v206
	v_and_b32_e32 v225, 0xffff0000, v206
	v_lshlrev_b32_e32 v226, 16, v210
	v_and_b32_e32 v227, 0xffff0000, v210
	v_mul_f32_e32 v126, v126, v212
	v_mul_f32_e32 v127, v127, v212
	v_mul_f32_e32 v122, v122, v212
	v_exp_f32_e32 v126, v126
	v_exp_f32_e32 v127, v127
	v_pk_fma_f32 v[124:125], v[120:121], v[226:227], v[224:225]
	v_mul_f32_e32 v120, v123, v212
	v_exp_f32_e32 v122, v122
	v_exp_f32_e32 v123, v120
	v_mul_f32_e32 v116, v116, v212
	v_mul_f32_e32 v117, v117, v212
	v_exp_f32_e32 v116, v116
	v_exp_f32_e32 v117, v117
	v_mul_f32_e32 v118, v118, v212
	v_mul_f32_e32 v119, v119, v212
	v_add_f32_e32 v126, 1.0, v126
	v_add_f32_e32 v127, 1.0, v127
	v_exp_f32_e32 v118, v118
	v_exp_f32_e32 v119, v119
	v_mul_f32_e32 v112, v112, v212
	v_mul_f32_e32 v113, v113, v212
	v_rcp_f32_e32 v126, v126
	v_rcp_f32_e32 v127, v127
	v_add_f32_e32 v122, 1.0, v122
	v_add_f32_e32 v123, 1.0, v123
	v_exp_f32_e32 v112, v112
	v_exp_f32_e32 v113, v113
	v_rcp_f32_e32 v232, v208
	v_rcp_f32_e32 v233, v233
	v_rcp_f32_e32 v122, v122
	v_rcp_f32_e32 v123, v123
	v_add_f32_e32 v116, 1.0, v116
	v_add_f32_e32 v117, 1.0, v117
	v_lshlrev_b32_e32 v206, 16, v207
	v_and_b32_e32 v207, 0xffff0000, v207
	v_lshlrev_b32_e32 v210, 16, v211
	v_and_b32_e32 v211, 0xffff0000, v211
	v_rcp_f32_e32 v116, v116
	v_rcp_f32_e32 v117, v117
	v_add_f32_e32 v118, 1.0, v118
	v_add_f32_e32 v119, 1.0, v119
	v_pk_fma_f32 v[126:127], v[126:127], v[210:211], v[206:207]
	v_lshlrev_b32_e32 v206, 16, v209
	v_and_b32_e32 v207, 0xffff0000, v209
	v_lshlrev_b32_e32 v208, 16, v213
	v_and_b32_e32 v209, 0xffff0000, v213
	v_rcp_f32_e32 v118, v118
	v_rcp_f32_e32 v119, v119
	v_add_f32_e32 v112, 1.0, v112
	v_add_f32_e32 v113, 1.0, v113
	v_pk_fma_f32 v[120:121], v[232:233], v[230:231], v[228:229]
	v_pk_fma_f32 v[122:123], v[122:123], v[208:209], v[206:207]
	v_lshl_add_u64 v[206:207], v[222:223], 2, s[2:3]
	v_rcp_f32_e32 v112, v112
; __device__ __forceinline__ float bflo(unsigned u) { return __uint_as_float(u << 16); }
; __device__ __forceinline__ float bfhi(unsigned u) { return __uint_as_float(u & 0xffff0000u); }
;     __device__ __forceinline__ void operator()(const Acc& acc, const Unit& u, int wr, int wc, int fr, int fq) const {
;     ...
;             for (int m = 0; m < 4; ++m) {
;                 const int row = u.pm * 256 + ai * 128 + wr * 64 + m * 16 + fr;
;                 const float rs = rsqrtf(rsv[m] * (1.0f / DM) + EPS) * -1.4426950408889634f;
; #pragma unroll
;                 for (int bj = 0; bj < 2; ++bj) {
;                     const size_t off = (size_t)row * DM + colbase + 32 * bj;
;                     f32x4 h0 = hv[m][bj][0], h1 = hv[m][bj][1];
;                     const u32x4 p4 = pw[m][bj];
;                     const f32x4 a0 = acc[ai][bj][m][0], a1 = acc[ai][bj][m][1];
;                     h0.x += bflo(p4.x) * __builtin_amdgcn_rcpf(1.0f + __builtin_amdgcn_exp2f(a0.x * rs));
;                     h0.y += bfhi(p4.x) * __builtin_amdgcn_rcpf(1.0f + __builtin_amdgcn_exp2f(a0.y * rs));
;                     h0.z += bflo(p4.y) * __builtin_amdgcn_rcpf(1.0f + __builtin_amdgcn_exp2f(a0.z * rs));
;                     h0.w += bfhi(p4.y) * __builtin_amdgcn_rcpf(1.0f + __builtin_amdgcn_exp2f(a0.w * rs));
;                     h1.x += bflo(p4.z) * __builtin_amdgcn_rcpf(1.0f + __builtin_amdgcn_exp2f(a1.x * rs));
;                     h1.y += bfhi(p4.z) * __builtin_amdgcn_rcpf(1.0f + __builtin_amdgcn_exp2f(a1.y * rs));
;                     h1.z += bflo(p4.w) * __builtin_amdgcn_rcpf(1.0f + __builtin_amdgcn_exp2f(a1.z * rs));
;                     h1.w += bfhi(p4.w) * __builtin_amdgcn_rcpf(1.0f + __builtin_amdgcn_exp2f(a1.w * rs));
;                     *(f32x4*)(out + off) = h0; *(f32x4*)(out + off + 4) = h1;
	v_rcp_f32_e32 v113, v113
	global_store_dwordx4 v[206:207], v[120:123], off offset:16
	global_store_dwordx4 v[206:207], v[124:127], off
	v_mul_f32_e32 v114, v114, v212
	v_lshlrev_b32_e32 v120, 16, v214
	v_and_b32_e32 v121, 0xffff0000, v214
	v_lshlrev_b32_e32 v122, 16, v218
	v_and_b32_e32 v123, 0xffff0000, v218
	v_pk_fma_f32 v[116:117], v[116:117], v[122:123], v[120:121]
	v_lshlrev_b32_e32 v120, 16, v215
	v_and_b32_e32 v121, 0xffff0000, v215
	v_lshlrev_b32_e32 v122, 16, v219
	v_and_b32_e32 v123, 0xffff0000, v219
	v_pk_fma_f32 v[118:119], v[118:119], v[122:123], v[120:121]
	v_lshlrev_b32_e32 v120, 16, v216
	v_and_b32_e32 v121, 0xffff0000, v216
	v_lshlrev_b32_e32 v122, 16, v220
	v_and_b32_e32 v123, 0xffff0000, v220
	v_pk_fma_f32 v[112:113], v[112:113], v[122:123], v[120:121]
	v_fmamk_f32 v123, v234, 0x3a000000, v205
	v_mul_f32_e32 v124, 0x4b800000, v123
	v_cmp_gt_f32_e32 vcc, s40, v123
	global_store_dwordx4 v[206:207], v[116:119], off offset:128
	v_mul_f32_e32 v115, v115, v212
	v_cndmask_b32_e32 v123, v123, v124, vcc
	v_rsq_f32_e32 v124, v123
	v_exp_f32_e32 v114, v114
	v_exp_f32_e32 v115, v115
	v_lshlrev_b32_e32 v120, 16, v217
	v_mul_f32_e32 v116, 0x45800000, v124
	v_cndmask_b32_e32 v116, v124, v116, vcc
	v_mul_f32_e32 v116, 0xbfb8aa3b, v116
	v_mul_f32_e32 v108, v108, v116
	v_mul_f32_e32 v109, v109, v116
	v_exp_f32_e32 v108, v108
	v_exp_f32_e32 v109, v109
	v_mul_f32_e32 v110, v110, v116
	v_mul_f32_e32 v111, v111, v116
	v_exp_f32_e32 v110, v110
	v_exp_f32_e32 v111, v111
	v_mul_f32_e32 v104, v104, v116
	v_mul_f32_e32 v105, v105, v116
	v_add_f32_e32 v114, 1.0, v114
	v_add_f32_e32 v115, 1.0, v115
	v_exp_f32_e32 v104, v104
	v_exp_f32_e32 v105, v105
	v_mul_f32_e32 v106, v106, v116
	v_mul_f32_e32 v107, v107, v116
	v_rcp_f32_e32 v114, v114
	v_rcp_f32_e32 v115, v115
	v_exp_f32_e32 v106, v106
	v_exp_f32_e32 v107, v107
	v_add_f32_e32 v108, 1.0, v108
	v_add_f32_e32 v109, 1.0, v109
	v_mul_f32_e32 v100, v100, v116
	v_mul_f32_e32 v101, v101, v116
	v_rcp_f32_e32 v108, v108
	v_rcp_f32_e32 v109, v109
	v_add_f32_e32 v110, 1.0, v110
	v_add_f32_e32 v111, 1.0, v111
	v_exp_f32_e32 v100, v100
	v_exp_f32_e32 v101, v101
	v_mul_f32_e32 v102, v102, v116
	v_mul_f32_e32 v103, v103, v116
	v_and_b32_e32 v121, 0xffff0000, v217
	v_lshlrev_b32_e32 v122, 16, v221
	v_and_b32_e32 v123, 0xffff0000, v221
	v_rcp_f32_e32 v110, v110
	v_rcp_f32_e32 v111, v111
	v_add_f32_e32 v104, 1.0, v104
	v_add_f32_e32 v105, 1.0, v105
	v_exp_f32_e32 v102, v102
	v_exp_f32_e32 v103, v103
	v_mul_f32_e32 v96, v96, v116
	v_mul_f32_e32 v97, v97, v116
	v_pk_fma_f32 v[114:115], v[114:115], v[122:123], v[120:121]
	v_rcp_f32_e32 v104, v104
	v_rcp_f32_e32 v105, v105
	v_add_f32_e32 v106, 1.0, v106
	v_add_f32_e32 v107, 1.0, v107
	v_exp_f32_e32 v96, v96
	v_exp_f32_e32 v97, v97
	global_store_dwordx4 v[206:207], v[112:115], off offset:144
	v_rcp_f32_e32 v106, v106
	v_rcp_f32_e32 v107, v107
	v_lshlrev_b32_e32 v112, 16, v172
	v_and_b32_e32 v113, 0xffff0000, v172
	v_lshlrev_b32_e32 v114, 16, v168
	v_and_b32_e32 v115, 0xffff0000, v168
	v_pk_fma_f32 v[108:109], v[108:109], v[114:115], v[112:113]
	v_lshlrev_b32_e32 v112, 16, v173
	v_and_b32_e32 v113, 0xffff0000, v173
	v_lshlrev_b32_e32 v114, 16, v169
	v_and_b32_e32 v115, 0xffff0000, v169
	v_add_f32_e32 v100, 1.0, v100
	v_add_f32_e32 v101, 1.0, v101
	v_pk_fma_f32 v[110:111], v[110:111], v[114:115], v[112:113]
	v_lshlrev_b32_e32 v112, 16, v174
	v_and_b32_e32 v113, 0xffff0000, v174
	v_lshlrev_b32_e32 v114, 16, v170
	v_and_b32_e32 v115, 0xffff0000, v170
	v_rcp_f32_e32 v100, v100
	v_rcp_f32_e32 v101, v101
	v_add_f32_e32 v102, 1.0, v102
	v_add_f32_e32 v103, 1.0, v103
	v_pk_fma_f32 v[104:105], v[104:105], v[114:115], v[112:113]
	v_lshlrev_b32_e32 v112, 16, v175
	v_and_b32_e32 v113, 0xffff0000, v175
	v_lshlrev_b32_e32 v114, 16, v171
	v_and_b32_e32 v115, 0xffff0000, v171
	v_rcp_f32_e32 v102, v102
	v_rcp_f32_e32 v103, v103
	v_add_f32_e32 v96, 1.0, v96
	v_add_f32_e32 v97, 1.0, v97
	v_pk_fma_f32 v[106:107], v[106:107], v[114:115], v[112:113]
	v_lshl_add_u64 v[112:113], v[198:199], 2, s[2:3]
	v_rcp_f32_e32 v96, v96
	v_rcp_f32_e32 v97, v97
	global_store_dwordx4 v[112:113], v[104:107], off offset:16
	global_store_dwordx4 v[112:113], v[108:111], off
	v_mul_f32_e32 v98, v98, v116
	v_lshlrev_b32_e32 v104, 16, v164
	v_and_b32_e32 v105, 0xffff0000, v164
	v_lshlrev_b32_e32 v106, 16, v160
	v_and_b32_e32 v107, 0xffff0000, v160
	v_pk_fma_f32 v[100:101], v[100:101], v[106:107], v[104:105]
	v_lshlrev_b32_e32 v104, 16, v165
	v_and_b32_e32 v105, 0xffff0000, v165
	v_lshlrev_b32_e32 v106, 16, v161
	v_and_b32_e32 v107, 0xffff0000, v161
	v_pk_fma_f32 v[102:103], v[102:103], v[106:107], v[104:105]
	v_lshlrev_b32_e32 v104, 16, v166
	v_and_b32_e32 v105, 0xffff0000, v166
	v_lshlrev_b32_e32 v106, 16, v162
	v_and_b32_e32 v107, 0xffff0000, v162
	v_pk_fma_f32 v[96:97], v[96:97], v[106:107], v[104:105]
	v_fmamk_f32 v107, v235, 0x3a000000, v205
	v_mul_f32_e32 v108, 0x4b800000, v107
	v_cmp_gt_f32_e32 vcc, s40, v107
	global_store_dwordx4 v[112:113], v[100:103], off offset:128
	v_mul_f32_e32 v99, v99, v116
	v_cndmask_b32_e32 v107, v107, v108, vcc
	v_rsq_f32_e32 v108, v107
	v_exp_f32_e32 v98, v98
	v_exp_f32_e32 v99, v99
	v_lshlrev_b32_e32 v104, 16, v167
	v_mul_f32_e32 v100, 0x45800000, v108
	v_cndmask_b32_e32 v100, v108, v100, vcc
	v_mul_f32_e32 v100, 0xbfb8aa3b, v100
	v_mul_f32_e32 v92, v92, v100
	v_mul_f32_e32 v93, v93, v100
	v_exp_f32_e32 v92, v92
	v_exp_f32_e32 v93, v93
	v_mul_f32_e32 v94, v94, v100
	v_mul_f32_e32 v95, v95, v100
	v_exp_f32_e32 v94, v94
	v_exp_f32_e32 v95, v95
	v_mul_f32_e32 v88, v88, v100
	v_mul_f32_e32 v89, v89, v100
	v_add_f32_e32 v98, 1.0, v98
	v_add_f32_e32 v99, 1.0, v99
	v_exp_f32_e32 v88, v88
; __device__ __forceinline__ float bflo(unsigned u) { return __uint_as_float(u << 16); }
; __device__ __forceinline__ float bfhi(unsigned u) { return __uint_as_float(u & 0xffff0000u); }
;     __device__ __forceinline__ void operator()(const Acc& acc, const Unit& u, int wr, int wc, int fr, int fq) const {
;     ...
;             for (int m = 0; m < 4; ++m) {
;                 const int row = u.pm * 256 + ai * 128 + wr * 64 + m * 16 + fr;
;                 const float rs = rsqrtf(rsv[m] * (1.0f / DM) + EPS) * -1.4426950408889634f;
; #pragma unroll
;                 for (int bj = 0; bj < 2; ++bj) {
;                     const size_t off = (size_t)row * DM + colbase + 32 * bj;
;                     f32x4 h0 = hv[m][bj][0], h1 = hv[m][bj][1];
;                     const u32x4 p4 = pw[m][bj];
;                     const f32x4 a0 = acc[ai][bj][m][0], a1 = acc[ai][bj][m][1];
;                     h0.x += bflo(p4.x) * __builtin_amdgcn_rcpf(1.0f + __builtin_amdgcn_exp2f(a0.x * rs));
;                     h0.y += bfhi(p4.x) * __builtin_amdgcn_rcpf(1.0f + __builtin_amdgcn_exp2f(a0.y * rs));
;                     h0.z += bflo(p4.y) * __builtin_amdgcn_rcpf(1.0f + __builtin_amdgcn_exp2f(a0.z * rs));
;                     h0.w += bfhi(p4.y) * __builtin_amdgcn_rcpf(1.0f + __builtin_amdgcn_exp2f(a0.w * rs));
;                     h1.x += bflo(p4.z) * __builtin_amdgcn_rcpf(1.0f + __builtin_amdgcn_exp2f(a1.x * rs));
;                     h1.y += bfhi(p4.z) * __builtin_amdgcn_rcpf(1.0f + __builtin_amdgcn_exp2f(a1.y * rs));
;                     h1.z += bflo(p4.w) * __builtin_amdgcn_rcpf(1.0f + __builtin_amdgcn_exp2f(a1.z * rs));
;                     h1.w += bfhi(p4.w) * __builtin_amdgcn_rcpf(1.0f + __builtin_amdgcn_exp2f(a1.w * rs));
;                     *(f32x4*)(out + off) = h0; *(f32x4*)(out + off + 4) = h1;
	v_exp_f32_e32 v89, v89
	v_mul_f32_e32 v90, v90, v100
	v_mul_f32_e32 v91, v91, v100
	v_rcp_f32_e32 v98, v98
	v_rcp_f32_e32 v99, v99
	v_exp_f32_e32 v90, v90
	v_exp_f32_e32 v91, v91
	v_add_f32_e32 v92, 1.0, v92
	v_add_f32_e32 v93, 1.0, v93
	v_mul_f32_e32 v84, v84, v100
	v_mul_f32_e32 v85, v85, v100
	v_rcp_f32_e32 v92, v92
	v_rcp_f32_e32 v93, v93
	v_add_f32_e32 v94, 1.0, v94
	v_add_f32_e32 v95, 1.0, v95
	v_exp_f32_e32 v84, v84
	v_exp_f32_e32 v85, v85
	v_mul_f32_e32 v86, v86, v100
	v_mul_f32_e32 v87, v87, v100
	v_and_b32_e32 v105, 0xffff0000, v167
	v_lshlrev_b32_e32 v106, 16, v163
	v_and_b32_e32 v107, 0xffff0000, v163
	v_rcp_f32_e32 v94, v94
	v_rcp_f32_e32 v95, v95
	v_add_f32_e32 v88, 1.0, v88
	v_add_f32_e32 v89, 1.0, v89
	v_exp_f32_e32 v86, v86
	v_exp_f32_e32 v87, v87
	v_mul_f32_e32 v80, v80, v100
	v_mul_f32_e32 v81, v81, v100
	v_pk_fma_f32 v[98:99], v[98:99], v[106:107], v[104:105]
	v_rcp_f32_e32 v88, v88
	v_rcp_f32_e32 v89, v89
	v_add_f32_e32 v90, 1.0, v90
	v_add_f32_e32 v91, 1.0, v91
	v_exp_f32_e32 v80, v80
	v_exp_f32_e32 v81, v81
	global_store_dwordx4 v[112:113], v[96:99], off offset:144
	v_rcp_f32_e32 v90, v90
	v_rcp_f32_e32 v91, v91
	v_lshlrev_b32_e32 v96, 16, v156
	v_and_b32_e32 v97, 0xffff0000, v156
	v_lshlrev_b32_e32 v98, 16, v152
	v_and_b32_e32 v99, 0xffff0000, v152
	v_pk_fma_f32 v[92:93], v[92:93], v[98:99], v[96:97]
	v_lshlrev_b32_e32 v96, 16, v157
	v_and_b32_e32 v97, 0xffff0000, v157
	v_lshlrev_b32_e32 v98, 16, v153
	v_and_b32_e32 v99, 0xffff0000, v153
	v_add_f32_e32 v84, 1.0, v84
	v_add_f32_e32 v85, 1.0, v85
	v_pk_fma_f32 v[94:95], v[94:95], v[98:99], v[96:97]
	v_lshlrev_b32_e32 v96, 16, v158
	v_and_b32_e32 v97, 0xffff0000, v158
	v_lshlrev_b32_e32 v98, 16, v154
	v_and_b32_e32 v99, 0xffff0000, v154
	v_rcp_f32_e32 v84, v84
	v_rcp_f32_e32 v85, v85
	v_add_f32_e32 v86, 1.0, v86
	v_add_f32_e32 v87, 1.0, v87
	v_pk_fma_f32 v[88:89], v[88:89], v[98:99], v[96:97]
	v_lshlrev_b32_e32 v96, 16, v159
	v_and_b32_e32 v97, 0xffff0000, v159
	v_lshlrev_b32_e32 v98, 16, v155
	v_and_b32_e32 v99, 0xffff0000, v155
	v_rcp_f32_e32 v86, v86
	v_rcp_f32_e32 v87, v87
	v_add_f32_e32 v80, 1.0, v80
	v_add_f32_e32 v81, 1.0, v81
	v_pk_fma_f32 v[90:91], v[90:91], v[98:99], v[96:97]
	v_lshl_add_u64 v[96:97], v[196:197], 2, s[2:3]
	v_rcp_f32_e32 v80, v80
	v_rcp_f32_e32 v81, v81
	global_store_dwordx4 v[96:97], v[88:91], off offset:16
	global_store_dwordx4 v[96:97], v[92:95], off
	v_mul_f32_e32 v82, v82, v100
	v_lshlrev_b32_e32 v88, 16, v148
	v_and_b32_e32 v89, 0xffff0000, v148
	v_lshlrev_b32_e32 v90, 16, v144
	v_and_b32_e32 v91, 0xffff0000, v144
	v_pk_fma_f32 v[84:85], v[84:85], v[90:91], v[88:89]
	v_lshlrev_b32_e32 v88, 16, v149
	v_and_b32_e32 v89, 0xffff0000, v149
	v_lshlrev_b32_e32 v90, 16, v145
	v_and_b32_e32 v91, 0xffff0000, v145
	v_pk_fma_f32 v[86:87], v[86:87], v[90:91], v[88:89]
	v_lshlrev_b32_e32 v88, 16, v150
	v_and_b32_e32 v89, 0xffff0000, v150
	v_lshlrev_b32_e32 v90, 16, v146
	v_and_b32_e32 v91, 0xffff0000, v146
	v_pk_fma_f32 v[80:81], v[80:81], v[90:91], v[88:89]
	v_fmamk_f32 v91, v191, 0x3a000000, v205
	v_mul_f32_e32 v92, 0x4b800000, v91
	v_cmp_gt_f32_e32 vcc, s40, v91
	global_store_dwordx4 v[96:97], v[84:87], off offset:128
	v_mul_f32_e32 v83, v83, v100
	v_cndmask_b32_e32 v91, v91, v92, vcc
	v_rsq_f32_e32 v92, v91
	v_exp_f32_e32 v82, v82
	v_exp_f32_e32 v83, v83
	v_lshlrev_b32_e32 v88, 16, v151
	v_mul_f32_e32 v84, 0x45800000, v92
	v_cndmask_b32_e32 v84, v92, v84, vcc
	v_mul_f32_e32 v84, 0xbfb8aa3b, v84
	v_mul_f32_e32 v76, v76, v84
	v_mul_f32_e32 v77, v77, v84
	v_exp_f32_e32 v76, v76
	v_exp_f32_e32 v77, v77
	v_mul_f32_e32 v78, v78, v84
	v_mul_f32_e32 v79, v79, v84
	v_exp_f32_e32 v78, v78
	v_exp_f32_e32 v79, v79
	v_mul_f32_e32 v72, v72, v84
	v_mul_f32_e32 v73, v73, v84
	v_add_f32_e32 v82, 1.0, v82
	v_add_f32_e32 v83, 1.0, v83
	v_exp_f32_e32 v72, v72
	v_exp_f32_e32 v73, v73
	v_mul_f32_e32 v74, v74, v84
	v_mul_f32_e32 v75, v75, v84
	v_rcp_f32_e32 v82, v82
	v_rcp_f32_e32 v83, v83
	v_exp_f32_e32 v74, v74
	v_exp_f32_e32 v75, v75
	v_add_f32_e32 v76, 1.0, v76
	v_add_f32_e32 v77, 1.0, v77
	v_mul_f32_e32 v68, v68, v84
	v_mul_f32_e32 v69, v69, v84
	v_rcp_f32_e32 v76, v76
	v_rcp_f32_e32 v77, v77
	v_add_f32_e32 v78, 1.0, v78
	v_add_f32_e32 v79, 1.0, v79
	v_exp_f32_e32 v68, v68
	v_exp_f32_e32 v69, v69
	v_mul_f32_e32 v70, v70, v84
	v_mul_f32_e32 v71, v71, v84
	v_and_b32_e32 v89, 0xffff0000, v151
	v_lshlrev_b32_e32 v90, 16, v147
	v_and_b32_e32 v91, 0xffff0000, v147
	v_rcp_f32_e32 v78, v78
; __device__ __forceinline__ float bflo(unsigned u) { return __uint_as_float(u << 16); }
;     __device__ __forceinline__ void operator()(const Acc& acc, const Unit& u, int wr, int wc, int fr, int fq) const {
;     ...
;             for (int m = 0; m < 4; ++m) { const int row = u.pm * 256 + ai * 128 + wr * 64 + m * 16 + fr; const size_t off = (size_t)row * DM + colbase;
;                 rsv[m] = rowss[row];
; #pragma unroll
;                 for (int bj = 0; bj < 2; ++bj) { const u32x4 hw = __builtin_nontemporal_load((const u32x4*)(hin + off + 32 * bj));
;                     hv[m][bj][0] = (f32x4){bflo(hw.x), bfhi(hw.x), bflo(hw.y), bfhi(hw.y)}; hv[m][bj][1] = (f32x4){bflo(hw.z), bfhi(hw.z), bflo(hw.w), bfhi(hw.w)};
;                     pw[m][bj] = __builtin_nontemporal_load((const u32x4*)(PP + off + 32 * bj)); } }
;     ...
;             for (int m = 0; m < 4; ++m) {
;                 const int row = u.pm * 256 + ai * 128 + wr * 64 + m * 16 + fr;
;                 const float rs = rsqrtf(rsv[m] * (1.0f / DM) + EPS) * -1.4426950408889634f;
; #pragma unroll
;                 for (int bj = 0; bj < 2; ++bj) {
;                     const size_t off = (size_t)row * DM + colbase + 32 * bj;
;                     f32x4 h0 = hv[m][bj][0], h1 = hv[m][bj][1];
;                     const u32x4 p4 = pw[m][bj];
;                     const f32x4 a0 = acc[ai][bj][m][0], a1 = acc[ai][bj][m][1];
;                     h0.x += bflo(p4.x) * __builtin_amdgcn_rcpf(1.0f + __builtin_amdgcn_exp2f(a0.x * rs));
;                     h0.y += bfhi(p4.x) * __builtin_amdgcn_rcpf(1.0f + __builtin_amdgcn_exp2f(a0.y * rs));
;                     h0.z += bflo(p4.y) * __builtin_amdgcn_rcpf(1.0f + __builtin_amdgcn_exp2f(a0.z * rs));
;                     h0.w += bfhi(p4.y) * __builtin_amdgcn_rcpf(1.0f + __builtin_amdgcn_exp2f(a0.w * rs));
;                     h1.x += bflo(p4.z) * __builtin_amdgcn_rcpf(1.0f + __builtin_amdgcn_exp2f(a1.x * rs));
;                     h1.y += bfhi(p4.z) * __builtin_amdgcn_rcpf(1.0f + __builtin_amdgcn_exp2f(a1.y * rs));
;                     h1.z += bflo(p4.w) * __builtin_amdgcn_rcpf(1.0f + __builtin_amdgcn_exp2f(a1.z * rs));
;                     h1.w += bfhi(p4.w) * __builtin_amdgcn_rcpf(1.0f + __builtin_amdgcn_exp2f(a1.w * rs));
;                     *(f32x4*)(out + off) = h0; *(f32x4*)(out + off + 4) = h1;
	v_rcp_f32_e32 v79, v79
	v_add_f32_e32 v72, 1.0, v72
	v_add_f32_e32 v73, 1.0, v73
	v_exp_f32_e32 v70, v70
	v_exp_f32_e32 v71, v71
	v_mul_f32_e32 v64, v64, v84
	v_mul_f32_e32 v65, v65, v84
	v_pk_fma_f32 v[82:83], v[82:83], v[90:91], v[88:89]
	v_rcp_f32_e32 v72, v72
	v_rcp_f32_e32 v73, v73
	v_add_f32_e32 v74, 1.0, v74
	v_add_f32_e32 v75, 1.0, v75
	v_exp_f32_e32 v64, v64
	v_exp_f32_e32 v65, v65
	v_mul_f32_e32 v66, v66, v84
	v_mul_f32_e32 v67, v67, v84
	global_store_dwordx4 v[96:97], v[80:83], off offset:144
	v_rcp_f32_e32 v74, v74
	v_rcp_f32_e32 v75, v75
	v_lshlrev_b32_e32 v80, 16, v140
	v_and_b32_e32 v81, 0xffff0000, v140
	v_lshlrev_b32_e32 v82, 16, v136
	v_and_b32_e32 v83, 0xffff0000, v136
	v_exp_f32_e32 v66, v66
	v_exp_f32_e32 v67, v67
	v_pk_fma_f32 v[76:77], v[76:77], v[82:83], v[80:81]
	v_lshlrev_b32_e32 v80, 16, v141
	v_and_b32_e32 v81, 0xffff0000, v141
	v_lshlrev_b32_e32 v82, 16, v137
	v_and_b32_e32 v83, 0xffff0000, v137
	v_add_f32_e32 v68, 1.0, v68
	v_add_f32_e32 v69, 1.0, v69
	v_pk_fma_f32 v[78:79], v[78:79], v[82:83], v[80:81]
	v_lshlrev_b32_e32 v80, 16, v142
	v_and_b32_e32 v81, 0xffff0000, v142
	v_lshlrev_b32_e32 v82, 16, v138
	v_and_b32_e32 v83, 0xffff0000, v138
	v_rcp_f32_e32 v68, v68
	v_rcp_f32_e32 v69, v69
	v_add_f32_e32 v70, 1.0, v70
	v_add_f32_e32 v71, 1.0, v71
	v_pk_fma_f32 v[72:73], v[72:73], v[82:83], v[80:81]
	v_lshlrev_b32_e32 v80, 16, v143
	v_and_b32_e32 v81, 0xffff0000, v143
	v_lshlrev_b32_e32 v82, 16, v139
	v_and_b32_e32 v83, 0xffff0000, v139
	v_rcp_f32_e32 v70, v70
	v_rcp_f32_e32 v71, v71
	v_add_f32_e32 v64, 1.0, v64
	v_add_f32_e32 v65, 1.0, v65
	v_pk_fma_f32 v[74:75], v[74:75], v[82:83], v[80:81]
	v_lshl_add_u64 v[80:81], v[194:195], 2, s[2:3]
	v_rcp_f32_e32 v64, v64
	v_rcp_f32_e32 v65, v65
	v_add_f32_e32 v66, 1.0, v66
	v_add_f32_e32 v67, 1.0, v67
	global_store_dwordx4 v[80:81], v[72:75], off offset:16
	v_rcp_f32_e32 v66, v66
	v_rcp_f32_e32 v67, v67
	v_lshlrev_b32_e32 v72, 16, v132
	v_and_b32_e32 v73, 0xffff0000, v132
	v_lshlrev_b32_e32 v74, 16, v128
	v_and_b32_e32 v75, 0xffff0000, v128
	v_pk_fma_f32 v[68:69], v[68:69], v[74:75], v[72:73]
	v_lshlrev_b32_e32 v72, 16, v133
	v_and_b32_e32 v73, 0xffff0000, v133
	v_lshlrev_b32_e32 v74, 16, v129
	v_and_b32_e32 v75, 0xffff0000, v129
	v_pk_fma_f32 v[70:71], v[70:71], v[74:75], v[72:73]
	v_lshlrev_b32_e32 v72, 16, v134
	v_and_b32_e32 v73, 0xffff0000, v134
	v_lshlrev_b32_e32 v74, 16, v130
	v_and_b32_e32 v75, 0xffff0000, v130
	v_pk_fma_f32 v[64:65], v[64:65], v[74:75], v[72:73]
	v_lshlrev_b32_e32 v72, 16, v135
	v_and_b32_e32 v73, 0xffff0000, v135
	v_lshlrev_b32_e32 v74, 16, v131
	v_and_b32_e32 v75, 0xffff0000, v131
	global_store_dwordx4 v[80:81], v[76:79], off
	v_pk_fma_f32 v[66:67], v[66:67], v[74:75], v[72:73]
	global_store_dwordx4 v[80:81], v[68:71], off offset:128
	global_store_dwordx4 v[80:81], v[64:67], off offset:144
	global_load_dword v68, v[192:193], off offset:512
	s_nop 0
	v_add_u32_e32 v64, 0x80, v190
	v_ashrrev_i32_e32 v65, 31, v64
	v_lshlrev_b64 v[64:65], 11, v[64:65]
	v_lshl_add_u64 v[136:137], v[64:65], 0, v[188:189]
	v_lshlrev_b64 v[64:65], 1, v[136:137]
	v_lshl_add_u64 v[66:67], s[6:7], 0, v[64:65]
	v_lshl_add_u64 v[64:65], s[8:9], 0, v[64:65]
	v_mov_b64_e32 v[124:125], v[248:249]
	v_mov_b64_e32 v[126:127], v[252:253]
	global_load_dwordx4 v[128:131], v[64:65], off nt
	v_mov_b64_e32 v[132:133], v[236:237]
	v_mov_b64_e32 v[134:135], v[238:239]
	global_load_dwordx4 v[112:115], v[64:65], off offset:64 nt
	v_add_u32_e32 v64, 0x90, v190
	v_ashrrev_i32_e32 v65, 31, v64
	v_lshlrev_b64 v[64:65], 11, v[64:65]
	v_lshl_add_u64 v[120:121], v[64:65], 0, v[188:189]
	v_lshlrev_b64 v[64:65], 1, v[120:121]
	v_lshl_add_u64 v[66:67], s[6:7], 0, v[64:65]
	v_lshl_add_u64 v[64:65], s[8:9], 0, v[64:65]
	v_mov_b64_e32 v[108:109], v[240:241]
	v_mov_b64_e32 v[110:111], v[250:251]
	v_mov_b32_e32 v100, 0x20000
	v_lshl_add_u32 v100, v200, 4, v100
	v_lshl_add_u32 v100, s79, 6, v100
	v_lshl_add_u32 v100, s86, 4, v100
	ds_read_b128 v[100:103], v100
	global_load_dwordx4 v[104:107], v[64:65], off nt
	global_load_dwordx4 v[96:99], v[64:65], off offset:64 nt
	v_add_u32_e32 v64, 0xa0, v190
	v_ashrrev_i32_e32 v65, 31, v64
	v_lshlrev_b64 v[64:65], 11, v[64:65]
	v_lshl_add_u64 v[118:119], v[64:65], 0, v[188:189]
	v_lshlrev_b64 v[64:65], 1, v[118:119]
	v_lshl_add_u64 v[66:67], s[6:7], 0, v[64:65]
	v_lshl_add_u64 v[64:65], s[8:9], 0, v[64:65]
	s_cmp_eq_u32 s79, 64
	s_cbranch_scc0 .Lhbk_r
	s_cmp_eq_u32 s86, 0xc0
	s_cbranch_scc1 .Lhbk_rl

; __device__ __forceinline__ float bflo(unsigned u) { return __uint_as_float(u << 16); }
;     __device__ __forceinline__ void operator()(const Acc& acc, const Unit& u, int wr, int wc, int fr, int fq) const {
;     ...
;             for (int m = 0; m < 4; ++m) { const int row = u.pm * 256 + ai * 128 + wr * 64 + m * 16 + fr; const size_t off = (size_t)row * DM + colbase;
;                 rsv[m] = rowss[row];
; #pragma unroll
;                 for (int bj = 0; bj < 2; ++bj) { const u32x4 hw = __builtin_nontemporal_load((const u32x4*)(hin + off + 32 * bj));
;                     hv[m][bj][0] = (f32x4){bflo(hw.x), bfhi(hw.x), bflo(hw.y), bfhi(hw.y)}; hv[m][bj][1] = (f32x4){bflo(hw.z), bfhi(hw.z), bflo(hw.w), bfhi(hw.w)};
;                     pw[m][bj] = __builtin_nontemporal_load((const u32x4*)(PP + off + 32 * bj)); } }
; #pragma unroll
;             for (int m = 0; m < 4; ++m) {
;                 const int row = u.pm * 256 + ai * 128 + wr * 64 + m * 16 + fr;
;                 const float rs = rsqrtf(rsv[m] * (1.0f / DM) + EPS) * -1.4426950408889634f;
; #pragma unroll
;                 for (int bj = 0; bj < 2; ++bj) {
;                     const size_t off = (size_t)row * DM + colbase + 32 * bj;
;                     f32x4 h0 = hv[m][bj][0], h1 = hv[m][bj][1];
;                     const u32x4 p4 = pw[m][bj];
;                     const f32x4 a0 = acc[ai][bj][m][0], a1 = acc[ai][bj][m][1];
;                     h0.x += bflo(p4.x) * __builtin_amdgcn_rcpf(1.0f + __builtin_amdgcn_exp2f(a0.x * rs));
;                     h0.y += bfhi(p4.x) * __builtin_amdgcn_rcpf(1.0f + __builtin_amdgcn_exp2f(a0.y * rs));
;                     h0.z += bflo(p4.y) * __builtin_amdgcn_rcpf(1.0f + __builtin_amdgcn_exp2f(a0.z * rs));
;                     h0.w += bfhi(p4.y) * __builtin_amdgcn_rcpf(1.0f + __builtin_amdgcn_exp2f(a0.w * rs));
;                     h1.x += bflo(p4.z) * __builtin_amdgcn_rcpf(1.0f + __builtin_amdgcn_exp2f(a1.x * rs));
;                     h1.y += bfhi(p4.z) * __builtin_amdgcn_rcpf(1.0f + __builtin_amdgcn_exp2f(a1.y * rs));
;                     h1.z += bflo(p4.w) * __builtin_amdgcn_rcpf(1.0f + __builtin_amdgcn_exp2f(a1.z * rs));
;                     h1.w += bfhi(p4.w) * __builtin_amdgcn_rcpf(1.0f + __builtin_amdgcn_exp2f(a1.w * rs));
;                     *(f32x4*)(out + off) = h0; *(f32x4*)(out + off + 4) = h1;
.Lhbk_rd:
	global_load_dwordx4 v[84:87], v[66:67], off offset:64 nt
	global_load_dwordx4 v[88:91], v[64:65], off nt
	global_load_dwordx4 v[80:83], v[64:65], off offset:64 nt
	global_load_dword v123, v[192:193], off offset:576
	global_load_dword v142, v[192:193], off offset:640
	global_load_dword v122, v[192:193], off offset:704
	v_add_u32_e32 v64, 0xb0, v190
	v_ashrrev_i32_e32 v65, 31, v64
	v_lshlrev_b64 v[64:65], 11, v[64:65]
	v_lshl_add_u64 v[116:117], v[64:65], 0, v[188:189]
	v_lshlrev_b64 v[64:65], 1, v[116:117]
	v_lshl_add_u64 v[66:67], s[6:7], 0, v[64:65]
	s_waitcnt vmcnt(0) lgkmcnt(0)
	v_fmamk_f32 v68, v68, 0x3a000000, v205
	v_mul_f32_e32 v69, 0x4b800000, v68
	v_cmp_gt_f32_e32 vcc, s40, v68
	v_lshlrev_b32_e32 v140, 16, v128
	s_nop 0
	v_cndmask_b32_e32 v68, v68, v69, vcc
	v_rsq_f32_e32 v70, v68
	v_lshl_add_u64 v[68:69], s[8:9], 0, v[64:65]
	v_lshlrev_b32_e32 v138, 16, v124
	v_and_b32_e32 v139, 0xffff0000, v124
	v_mul_f32_e32 v71, 0x45800000, v70
	v_cndmask_b32_e32 v70, v70, v71, vcc
	v_mul_f32_e32 v143, 0xbfb8aa3b, v70
	v_mul_f32_e32 v62, v62, v143
	v_mul_f32_e32 v63, v63, v143
	v_exp_f32_e32 v62, v62
	v_exp_f32_e32 v63, v63
	v_mul_f32_e32 v56, v56, v143
	v_mul_f32_e32 v57, v57, v143
	v_exp_f32_e32 v56, v56
	v_exp_f32_e32 v57, v57
	v_mul_f32_e32 v58, v58, v143
	v_mul_f32_e32 v59, v59, v143
	v_exp_f32_e32 v58, v58
	v_exp_f32_e32 v59, v59
	v_mul_f32_e32 v52, v52, v143
	v_mul_f32_e32 v53, v53, v143
	v_add_f32_e32 v62, 1.0, v62
	v_add_f32_e32 v63, 1.0, v63
	v_exp_f32_e32 v52, v52
	v_exp_f32_e32 v53, v53
	v_mul_f32_e32 v54, v54, v143
	v_mul_f32_e32 v55, v55, v143
	v_mul_f32_e32 v60, v60, v143
	v_mul_f32_e32 v61, v61, v143
	v_rcp_f32_e32 v62, v62
	v_rcp_f32_e32 v63, v63
	v_add_f32_e32 v56, 1.0, v56
	v_add_f32_e32 v57, 1.0, v57
	v_exp_f32_e32 v54, v54
	v_exp_f32_e32 v55, v55
	v_mul_f32_e32 v48, v48, v143
	v_mul_f32_e32 v49, v49, v143
	v_exp_f32_e32 v60, v60
	v_exp_f32_e32 v61, v61
	v_rcp_f32_e32 v56, v56
	v_rcp_f32_e32 v57, v57
	v_add_f32_e32 v58, 1.0, v58
	v_add_f32_e32 v59, 1.0, v59
	v_exp_f32_e32 v48, v48
	v_exp_f32_e32 v49, v49
	v_rcp_f32_e32 v58, v58
	v_rcp_f32_e32 v59, v59
	v_and_b32_e32 v141, 0xffff0000, v128
	v_lshlrev_b32_e32 v124, 16, v125
	v_and_b32_e32 v125, 0xffff0000, v125
	v_lshlrev_b32_e32 v128, 16, v129
	v_and_b32_e32 v129, 0xffff0000, v129
	v_add_f32_e32 v52, 1.0, v52
	v_add_f32_e32 v53, 1.0, v53
	global_load_dwordx4 v[72:75], v[66:67], off nt
	s_nop 0
	global_load_dwordx4 v[64:67], v[66:67], off offset:64 nt
	s_nop 0
	global_load_dwordx4 v[76:79], v[68:69], off nt
	s_nop 0
	global_load_dwordx4 v[68:71], v[68:69], off offset:64 nt
	v_pk_fma_f32 v[62:63], v[62:63], v[128:129], v[124:125]
	v_lshlrev_b32_e32 v124, 16, v126
	v_and_b32_e32 v125, 0xffff0000, v126
	v_lshlrev_b32_e32 v128, 16, v130
	v_and_b32_e32 v129, 0xffff0000, v130
	v_rcp_f32_e32 v52, v52
	v_rcp_f32_e32 v53, v53
	v_add_f32_e32 v54, 1.0, v54
	v_add_f32_e32 v55, 1.0, v55
	v_add_f32_e32 v60, 1.0, v60
	v_add_f32_e32 v61, 1.0, v61
	v_pk_fma_f32 v[56:57], v[56:57], v[128:129], v[124:125]
	v_lshlrev_b32_e32 v124, 16, v127
	v_and_b32_e32 v125, 0xffff0000, v127
	v_lshlrev_b32_e32 v126, 16, v131
	v_and_b32_e32 v127, 0xffff0000, v131
	v_rcp_f32_e32 v54, v54
	v_rcp_f32_e32 v55, v55
	v_add_f32_e32 v48, 1.0, v48
	v_add_f32_e32 v49, 1.0, v49
	v_rcp_f32_e32 v60, v60
	v_rcp_f32_e32 v61, v61
	v_pk_fma_f32 v[58:59], v[58:59], v[126:127], v[124:125]
	v_lshl_add_u64 v[124:125], v[136:137], 2, s[2:3]
	v_rcp_f32_e32 v48, v48
	v_rcp_f32_e32 v49, v49
	global_store_dwordx4 v[124:125], v[56:59], off offset:16
	v_pk_fma_f32 v[60:61], v[60:61], v[140:141], v[138:139]
	global_store_dwordx4 v[124:125], v[60:63], off
	v_lshlrev_b32_e32 v56, 16, v132
	v_and_b32_e32 v57, 0xffff0000, v132
	v_lshlrev_b32_e32 v58, 16, v112
	v_and_b32_e32 v59, 0xffff0000, v112
	v_pk_fma_f32 v[52:53], v[52:53], v[58:59], v[56:57]
	v_lshlrev_b32_e32 v56, 16, v133
	v_and_b32_e32 v57, 0xffff0000, v133
	v_lshlrev_b32_e32 v58, 16, v113
	v_and_b32_e32 v59, 0xffff0000, v113
	v_pk_fma_f32 v[54:55], v[54:55], v[58:59], v[56:57]
	v_lshlrev_b32_e32 v56, 16, v134
	v_and_b32_e32 v57, 0xffff0000, v134
	v_lshlrev_b32_e32 v58, 16, v114
	v_and_b32_e32 v59, 0xffff0000, v114
	v_pk_fma_f32 v[48:49], v[48:49], v[58:59], v[56:57]
	v_fmamk_f32 v59, v123, 0x3a000000, v205
	v_mul_f32_e32 v60, 0x4b800000, v59
	v_cmp_gt_f32_e32 vcc, s40, v59
	global_store_dwordx4 v[124:125], v[52:55], off offset:128
	v_mul_f32_e32 v50, v50, v143
	v_cndmask_b32_e32 v59, v59, v60, vcc
	v_rsq_f32_e32 v60, v59
	v_mul_f32_e32 v51, v51, v143
	v_exp_f32_e32 v50, v50
	v_exp_f32_e32 v51, v51
	v_mul_f32_e32 v52, 0x45800000, v60
	v_cndmask_b32_e32 v52, v60, v52, vcc
	v_mul_f32_e32 v52, 0xbfb8aa3b, v52
	v_mul_f32_e32 v44, v44, v52
	v_mul_f32_e32 v45, v45, v52
	v_exp_f32_e32 v44, v44
	v_exp_f32_e32 v45, v45
	v_mul_f32_e32 v46, v46, v52
	v_mul_f32_e32 v47, v47, v52
	v_exp_f32_e32 v46, v46
	v_exp_f32_e32 v47, v47
	v_mul_f32_e32 v40, v40, v52
	v_mul_f32_e32 v41, v41, v52
	v_add_f32_e32 v50, 1.0, v50
	v_add_f32_e32 v51, 1.0, v51
	v_exp_f32_e32 v40, v40
	v_exp_f32_e32 v41, v41
	v_mul_f32_e32 v42, v42, v52
	v_mul_f32_e32 v43, v43, v52
	v_rcp_f32_e32 v50, v50
	v_rcp_f32_e32 v51, v51
	v_exp_f32_e32 v42, v42
	v_exp_f32_e32 v43, v43
	v_add_f32_e32 v44, 1.0, v44
	v_add_f32_e32 v45, 1.0, v45
	v_mul_f32_e32 v36, v36, v52
	v_mul_f32_e32 v37, v37, v52
	v_rcp_f32_e32 v44, v44
	v_rcp_f32_e32 v45, v45
	v_add_f32_e32 v46, 1.0, v46
	v_add_f32_e32 v47, 1.0, v47
	v_exp_f32_e32 v36, v36
	v_exp_f32_e32 v37, v37
	v_mul_f32_e32 v38, v38, v52
	v_mul_f32_e32 v39, v39, v52
	v_lshlrev_b32_e32 v56, 16, v135
	v_and_b32_e32 v57, 0xffff0000, v135
	v_lshlrev_b32_e32 v58, 16, v115
	v_and_b32_e32 v59, 0xffff0000, v115
; __device__ __forceinline__ float bflo(unsigned u) { return __uint_as_float(u << 16); }
; __device__ __forceinline__ float bfhi(unsigned u) { return __uint_as_float(u & 0xffff0000u); }
;     __device__ __forceinline__ void operator()(const Acc& acc, const Unit& u, int wr, int wc, int fr, int fq) const {
;     ...
;             for (int m = 0; m < 4; ++m) {
;                 const int row = u.pm * 256 + ai * 128 + wr * 64 + m * 16 + fr;
;                 const float rs = rsqrtf(rsv[m] * (1.0f / DM) + EPS) * -1.4426950408889634f;
; #pragma unroll
;                 for (int bj = 0; bj < 2; ++bj) {
;                     const size_t off = (size_t)row * DM + colbase + 32 * bj;
;                     f32x4 h0 = hv[m][bj][0], h1 = hv[m][bj][1];
;                     const u32x4 p4 = pw[m][bj];
;                     const f32x4 a0 = acc[ai][bj][m][0], a1 = acc[ai][bj][m][1];
;                     h0.x += bflo(p4.x) * __builtin_amdgcn_rcpf(1.0f + __builtin_amdgcn_exp2f(a0.x * rs));
;                     h0.y += bfhi(p4.x) * __builtin_amdgcn_rcpf(1.0f + __builtin_amdgcn_exp2f(a0.y * rs));
;                     h0.z += bflo(p4.y) * __builtin_amdgcn_rcpf(1.0f + __builtin_amdgcn_exp2f(a0.z * rs));
;                     h0.w += bfhi(p4.y) * __builtin_amdgcn_rcpf(1.0f + __builtin_amdgcn_exp2f(a0.w * rs));
;                     h1.x += bflo(p4.z) * __builtin_amdgcn_rcpf(1.0f + __builtin_amdgcn_exp2f(a1.x * rs));
;                     h1.y += bfhi(p4.z) * __builtin_amdgcn_rcpf(1.0f + __builtin_amdgcn_exp2f(a1.y * rs));
;                     h1.z += bflo(p4.w) * __builtin_amdgcn_rcpf(1.0f + __builtin_amdgcn_exp2f(a1.z * rs));
;                     h1.w += bfhi(p4.w) * __builtin_amdgcn_rcpf(1.0f + __builtin_amdgcn_exp2f(a1.w * rs));
;                     *(f32x4*)(out + off) = h0; *(f32x4*)(out + off + 4) = h1;
	v_rcp_f32_e32 v46, v46
	v_rcp_f32_e32 v47, v47
	v_add_f32_e32 v40, 1.0, v40
	v_add_f32_e32 v41, 1.0, v41
	v_exp_f32_e32 v38, v38
	v_exp_f32_e32 v39, v39
	v_mul_f32_e32 v32, v32, v52
	v_mul_f32_e32 v33, v33, v52
	v_pk_fma_f32 v[50:51], v[50:51], v[58:59], v[56:57]
	v_rcp_f32_e32 v40, v40
	v_rcp_f32_e32 v41, v41
	v_add_f32_e32 v42, 1.0, v42
	v_add_f32_e32 v43, 1.0, v43
	v_exp_f32_e32 v32, v32
	v_exp_f32_e32 v33, v33
	global_store_dwordx4 v[124:125], v[48:51], off offset:144
	v_rcp_f32_e32 v42, v42
	v_rcp_f32_e32 v43, v43
	v_lshlrev_b32_e32 v48, 16, v108
	v_and_b32_e32 v49, 0xffff0000, v108
	v_lshlrev_b32_e32 v50, 16, v104
	v_and_b32_e32 v51, 0xffff0000, v104
	v_pk_fma_f32 v[44:45], v[44:45], v[50:51], v[48:49]
	v_lshlrev_b32_e32 v48, 16, v109
	v_and_b32_e32 v49, 0xffff0000, v109
	v_lshlrev_b32_e32 v50, 16, v105
	v_and_b32_e32 v51, 0xffff0000, v105
	v_add_f32_e32 v36, 1.0, v36
	v_add_f32_e32 v37, 1.0, v37
	v_pk_fma_f32 v[46:47], v[46:47], v[50:51], v[48:49]
	v_lshlrev_b32_e32 v48, 16, v110
	v_and_b32_e32 v49, 0xffff0000, v110
	v_lshlrev_b32_e32 v50, 16, v106
	v_and_b32_e32 v51, 0xffff0000, v106
	v_rcp_f32_e32 v36, v36
	v_rcp_f32_e32 v37, v37
	v_add_f32_e32 v38, 1.0, v38
	v_add_f32_e32 v39, 1.0, v39
	v_pk_fma_f32 v[40:41], v[40:41], v[50:51], v[48:49]
	v_lshlrev_b32_e32 v48, 16, v111
	v_and_b32_e32 v49, 0xffff0000, v111
	v_lshlrev_b32_e32 v50, 16, v107
	v_and_b32_e32 v51, 0xffff0000, v107
	v_rcp_f32_e32 v38, v38
	v_rcp_f32_e32 v39, v39
	v_add_f32_e32 v32, 1.0, v32
	v_add_f32_e32 v33, 1.0, v33
	v_pk_fma_f32 v[42:43], v[42:43], v[50:51], v[48:49]
	v_lshl_add_u64 v[48:49], v[120:121], 2, s[2:3]
	v_rcp_f32_e32 v32, v32
	v_rcp_f32_e32 v33, v33
	global_store_dwordx4 v[48:49], v[40:43], off offset:16
	global_store_dwordx4 v[48:49], v[44:47], off
	v_mul_f32_e32 v34, v34, v52
	v_lshlrev_b32_e32 v40, 16, v100
	v_and_b32_e32 v41, 0xffff0000, v100
	v_lshlrev_b32_e32 v42, 16, v96
	v_and_b32_e32 v43, 0xffff0000, v96
	v_pk_fma_f32 v[36:37], v[36:37], v[42:43], v[40:41]
	v_lshlrev_b32_e32 v40, 16, v101
	v_and_b32_e32 v41, 0xffff0000, v101
	v_lshlrev_b32_e32 v42, 16, v97
	v_and_b32_e32 v43, 0xffff0000, v97
	v_pk_fma_f32 v[38:39], v[38:39], v[42:43], v[40:41]
	v_lshlrev_b32_e32 v40, 16, v102
	v_and_b32_e32 v41, 0xffff0000, v102
	v_lshlrev_b32_e32 v42, 16, v98
	v_and_b32_e32 v43, 0xffff0000, v98
	v_pk_fma_f32 v[32:33], v[32:33], v[42:43], v[40:41]
	v_fmamk_f32 v43, v142, 0x3a000000, v205
	v_mul_f32_e32 v44, 0x4b800000, v43
	v_cmp_gt_f32_e32 vcc, s40, v43
	global_store_dwordx4 v[48:49], v[36:39], off offset:128
	v_mul_f32_e32 v35, v35, v52
	v_cndmask_b32_e32 v43, v43, v44, vcc
	v_rsq_f32_e32 v44, v43
	v_exp_f32_e32 v34, v34
	v_exp_f32_e32 v35, v35
	v_lshlrev_b32_e32 v40, 16, v103
	v_mul_f32_e32 v36, 0x45800000, v44
	v_cndmask_b32_e32 v36, v44, v36, vcc
	v_mul_f32_e32 v36, 0xbfb8aa3b, v36
	v_mul_f32_e32 v28, v28, v36
	v_mul_f32_e32 v29, v29, v36
	v_exp_f32_e32 v28, v28
	v_exp_f32_e32 v29, v29
	v_mul_f32_e32 v30, v30, v36
	v_mul_f32_e32 v31, v31, v36
	v_exp_f32_e32 v30, v30
	v_exp_f32_e32 v31, v31
	v_mul_f32_e32 v24, v24, v36
	v_mul_f32_e32 v25, v25, v36
	v_add_f32_e32 v34, 1.0, v34
	v_add_f32_e32 v35, 1.0, v35
	v_exp_f32_e32 v24, v24
	v_exp_f32_e32 v25, v25
	v_mul_f32_e32 v26, v26, v36
	v_mul_f32_e32 v27, v27, v36
	v_rcp_f32_e32 v34, v34
	v_rcp_f32_e32 v35, v35
	v_exp_f32_e32 v26, v26
	v_exp_f32_e32 v27, v27
	v_add_f32_e32 v28, 1.0, v28
	v_add_f32_e32 v29, 1.0, v29
	v_mul_f32_e32 v20, v20, v36
	v_mul_f32_e32 v21, v21, v36
	v_rcp_f32_e32 v28, v28
	v_rcp_f32_e32 v29, v29
	v_add_f32_e32 v30, 1.0, v30
	v_add_f32_e32 v31, 1.0, v31
	v_exp_f32_e32 v20, v20
	v_exp_f32_e32 v21, v21
	v_mul_f32_e32 v22, v22, v36
	v_mul_f32_e32 v23, v23, v36
	v_and_b32_e32 v41, 0xffff0000, v103
	v_lshlrev_b32_e32 v42, 16, v99
	v_and_b32_e32 v43, 0xffff0000, v99
	v_rcp_f32_e32 v30, v30
	v_rcp_f32_e32 v31, v31
	v_add_f32_e32 v24, 1.0, v24
	v_add_f32_e32 v25, 1.0, v25
	v_exp_f32_e32 v22, v22
	v_exp_f32_e32 v23, v23
	v_mul_f32_e32 v16, v16, v36
	v_mul_f32_e32 v17, v17, v36
	v_pk_fma_f32 v[34:35], v[34:35], v[42:43], v[40:41]
	v_rcp_f32_e32 v24, v24
	v_rcp_f32_e32 v25, v25
	v_add_f32_e32 v26, 1.0, v26
	v_add_f32_e32 v27, 1.0, v27
	v_exp_f32_e32 v16, v16
	v_exp_f32_e32 v17, v17
	global_store_dwordx4 v[48:49], v[32:35], off offset:144
	v_rcp_f32_e32 v26, v26
	v_rcp_f32_e32 v27, v27
	v_lshlrev_b32_e32 v32, 16, v92
	v_and_b32_e32 v33, 0xffff0000, v92
	v_lshlrev_b32_e32 v34, 16, v88
	v_and_b32_e32 v35, 0xffff0000, v88
	v_pk_fma_f32 v[28:29], v[28:29], v[34:35], v[32:33]
	v_lshlrev_b32_e32 v32, 16, v93
	v_and_b32_e32 v33, 0xffff0000, v93
	v_lshlrev_b32_e32 v34, 16, v89
	v_and_b32_e32 v35, 0xffff0000, v89
	v_add_f32_e32 v20, 1.0, v20
	v_add_f32_e32 v21, 1.0, v21
	v_pk_fma_f32 v[30:31], v[30:31], v[34:35], v[32:33]
	v_lshlrev_b32_e32 v32, 16, v94
	v_and_b32_e32 v33, 0xffff0000, v94
	v_lshlrev_b32_e32 v34, 16, v90
	v_and_b32_e32 v35, 0xffff0000, v90
	v_rcp_f32_e32 v20, v20
	v_rcp_f32_e32 v21, v21
	v_add_f32_e32 v22, 1.0, v22
	v_add_f32_e32 v23, 1.0, v23
	v_pk_fma_f32 v[24:25], v[24:25], v[34:35], v[32:33]
	v_lshlrev_b32_e32 v32, 16, v95
	v_and_b32_e32 v33, 0xffff0000, v95
	v_lshlrev_b32_e32 v34, 16, v91
	v_and_b32_e32 v35, 0xffff0000, v91
	v_rcp_f32_e32 v22, v22
	v_rcp_f32_e32 v23, v23
; template <class Epi, bool ALIGN_EPI>
; __device__ __forceinline__ void gemm_phase(LAS unsigned char* lds, const Gemm g, const StaticOrder& S, const Epi& E, const int wid) {
;     ...
;     for (;;) {
;         const bool has_next = S.next(ui + 1, nxt);
;         const char* nA = has_next ? (const char*)g.A + (size_t)nxt.pm * tstep : cA; const char* nB = has_next ? (const char*)g.Bt + (size_t)nxt.pn * tstep : cB;
;         for (int t = 0; t < nt; t += 2) {
;             const bool last = (t == nt - 2);
;             const char* a1 = cA + (size_t)(t + 1) * kstep;
;             const char* a2 = last ? nA : cA + (size_t)(t + 2) * kstep; const char* b2 = last ? nB : cB + (size_t)(t + 2) * kstep;
;             const char* a3 = a2 + kstep; const char* b3 = b2 + kstep;
;     __device__ __forceinline__ void operator()(const Acc& acc, const Unit& u, int wr, int wc, int fr, int fq) const {
;     ...
;             for (int m = 0; m < 4; ++m) {
;                 const int row = u.pm * 256 + ai * 128 + wr * 64 + m * 16 + fr;
;                 const float rs = rsqrtf(rsv[m] * (1.0f / DM) + EPS) * -1.4426950408889634f;
; #pragma unroll
;                 for (int bj = 0; bj < 2; ++bj) {
;                     const size_t off = (size_t)row * DM + colbase + 32 * bj;
;                     f32x4 h0 = hv[m][bj][0], h1 = hv[m][bj][1];
;                     const u32x4 p4 = pw[m][bj];
;                     const f32x4 a0 = acc[ai][bj][m][0], a1 = acc[ai][bj][m][1];
;                     h0.x += bflo(p4.x) * __builtin_amdgcn_rcpf(1.0f + __builtin_amdgcn_exp2f(a0.x * rs));
;                     h0.y += bfhi(p4.x) * __builtin_amdgcn_rcpf(1.0f + __builtin_amdgcn_exp2f(a0.y * rs));
;                     h0.z += bflo(p4.y) * __builtin_amdgcn_rcpf(1.0f + __builtin_amdgcn_exp2f(a0.z * rs));
;                     h0.w += bfhi(p4.y) * __builtin_amdgcn_rcpf(1.0f + __builtin_amdgcn_exp2f(a0.w * rs));
;                     h1.x += bflo(p4.z) * __builtin_amdgcn_rcpf(1.0f + __builtin_amdgcn_exp2f(a1.x * rs));
;                     h1.y += bfhi(p4.z) * __builtin_amdgcn_rcpf(1.0f + __builtin_amdgcn_exp2f(a1.y * rs));
;                     h1.z += bflo(p4.w) * __builtin_amdgcn_rcpf(1.0f + __builtin_amdgcn_exp2f(a1.z * rs));
;                     h1.w += bfhi(p4.w) * __builtin_amdgcn_rcpf(1.0f + __builtin_amdgcn_exp2f(a1.w * rs));
;                     *(f32x4*)(out + off) = h0; *(f32x4*)(out + off + 4) = h1;
	v_add_f32_e32 v16, 1.0, v16
	v_add_f32_e32 v17, 1.0, v17
	v_pk_fma_f32 v[26:27], v[26:27], v[34:35], v[32:33]
	v_lshl_add_u64 v[32:33], v[118:119], 2, s[2:3]
	v_rcp_f32_e32 v16, v16
	v_rcp_f32_e32 v17, v17
	global_store_dwordx4 v[32:33], v[24:27], off offset:16
	global_store_dwordx4 v[32:33], v[28:31], off
	v_mul_f32_e32 v18, v18, v36
	v_lshlrev_b32_e32 v24, 16, v84
	v_and_b32_e32 v25, 0xffff0000, v84
	v_lshlrev_b32_e32 v26, 16, v80
	v_and_b32_e32 v27, 0xffff0000, v80
	v_pk_fma_f32 v[20:21], v[20:21], v[26:27], v[24:25]
	v_lshlrev_b32_e32 v24, 16, v85
	v_and_b32_e32 v25, 0xffff0000, v85
	v_lshlrev_b32_e32 v26, 16, v81
	v_and_b32_e32 v27, 0xffff0000, v81
	v_pk_fma_f32 v[22:23], v[22:23], v[26:27], v[24:25]
	v_lshlrev_b32_e32 v24, 16, v86
	v_and_b32_e32 v25, 0xffff0000, v86
	v_lshlrev_b32_e32 v26, 16, v82
	v_and_b32_e32 v27, 0xffff0000, v82
	v_pk_fma_f32 v[16:17], v[16:17], v[26:27], v[24:25]
	v_fmamk_f32 v27, v122, 0x3a000000, v205
	v_mul_f32_e32 v28, 0x4b800000, v27
	v_cmp_gt_f32_e32 vcc, s40, v27
	global_store_dwordx4 v[32:33], v[20:23], off offset:128
	v_mul_f32_e32 v19, v19, v36
	v_cndmask_b32_e32 v27, v27, v28, vcc
	v_rsq_f32_e32 v28, v27
	v_exp_f32_e32 v18, v18
	v_exp_f32_e32 v19, v19
	v_lshlrev_b32_e32 v24, 16, v87
	v_mul_f32_e32 v20, 0x45800000, v28
	v_cndmask_b32_e32 v20, v28, v20, vcc
	v_mul_f32_e32 v20, 0xbfb8aa3b, v20
	v_mul_f32_e32 v12, v12, v20
	v_mul_f32_e32 v13, v13, v20
	v_exp_f32_e32 v12, v12
	v_exp_f32_e32 v13, v13
	v_mul_f32_e32 v14, v14, v20
	v_mul_f32_e32 v15, v15, v20
	v_exp_f32_e32 v14, v14
	v_exp_f32_e32 v15, v15
	v_mul_f32_e32 v8, v8, v20
	v_mul_f32_e32 v9, v9, v20
	v_add_f32_e32 v18, 1.0, v18
	v_add_f32_e32 v19, 1.0, v19
	v_exp_f32_e32 v8, v8
	v_exp_f32_e32 v9, v9
	v_mul_f32_e32 v10, v10, v20
	v_mul_f32_e32 v11, v11, v20
	v_rcp_f32_e32 v18, v18
	v_rcp_f32_e32 v19, v19
	v_exp_f32_e32 v10, v10
	v_exp_f32_e32 v11, v11
	v_add_f32_e32 v12, 1.0, v12
	v_add_f32_e32 v13, 1.0, v13
	v_mul_f32_e32 v4, v4, v20
	v_mul_f32_e32 v5, v5, v20
	v_rcp_f32_e32 v12, v12
	v_rcp_f32_e32 v13, v13
	v_add_f32_e32 v14, 1.0, v14
	v_add_f32_e32 v15, 1.0, v15
	v_exp_f32_e32 v4, v4
	v_exp_f32_e32 v5, v5
	v_mul_f32_e32 v6, v6, v20
	v_mul_f32_e32 v7, v7, v20
	v_and_b32_e32 v25, 0xffff0000, v87
	v_lshlrev_b32_e32 v26, 16, v83
	v_and_b32_e32 v27, 0xffff0000, v83
	v_rcp_f32_e32 v14, v14
	v_rcp_f32_e32 v15, v15
	v_add_f32_e32 v8, 1.0, v8
	v_add_f32_e32 v9, 1.0, v9
	v_exp_f32_e32 v6, v6
	v_exp_f32_e32 v7, v7
	v_mul_f32_e32 v0, v0, v20
	v_mul_f32_e32 v1, v1, v20
	v_pk_fma_f32 v[18:19], v[18:19], v[26:27], v[24:25]
	v_rcp_f32_e32 v8, v8
	v_rcp_f32_e32 v9, v9
	v_add_f32_e32 v10, 1.0, v10
	v_add_f32_e32 v11, 1.0, v11
	v_exp_f32_e32 v0, v0
	v_exp_f32_e32 v1, v1
	v_mul_f32_e32 v2, v2, v20
	v_mul_f32_e32 v3, v3, v20
	global_store_dwordx4 v[32:33], v[16:19], off offset:144
	v_rcp_f32_e32 v10, v10
	v_rcp_f32_e32 v11, v11
	s_waitcnt vmcnt(0) lgkmcnt(0)
	v_lshlrev_b32_e32 v16, 16, v72
	v_and_b32_e32 v17, 0xffff0000, v72
	v_lshlrev_b32_e32 v18, 16, v76
	v_and_b32_e32 v19, 0xffff0000, v76
	v_exp_f32_e32 v2, v2
	v_exp_f32_e32 v3, v3
	v_pk_fma_f32 v[12:13], v[12:13], v[18:19], v[16:17]
	v_lshlrev_b32_e32 v16, 16, v73
	v_and_b32_e32 v17, 0xffff0000, v73
	v_lshlrev_b32_e32 v18, 16, v77
	v_and_b32_e32 v19, 0xffff0000, v77
	v_add_f32_e32 v4, 1.0, v4
	v_add_f32_e32 v5, 1.0, v5
	v_pk_fma_f32 v[14:15], v[14:15], v[18:19], v[16:17]
	v_lshlrev_b32_e32 v16, 16, v74
	v_and_b32_e32 v17, 0xffff0000, v74
	v_lshlrev_b32_e32 v18, 16, v78
	v_and_b32_e32 v19, 0xffff0000, v78
	v_rcp_f32_e32 v4, v4
	v_rcp_f32_e32 v5, v5
	v_add_f32_e32 v6, 1.0, v6
	v_add_f32_e32 v7, 1.0, v7
	v_pk_fma_f32 v[8:9], v[8:9], v[18:19], v[16:17]
	v_lshlrev_b32_e32 v16, 16, v75
	v_and_b32_e32 v17, 0xffff0000, v75
	v_lshlrev_b32_e32 v18, 16, v79
	v_and_b32_e32 v19, 0xffff0000, v79
	v_rcp_f32_e32 v6, v6
	v_rcp_f32_e32 v7, v7
	v_add_f32_e32 v0, 1.0, v0
	v_add_f32_e32 v1, 1.0, v1
	v_pk_fma_f32 v[10:11], v[10:11], v[18:19], v[16:17]
	v_lshl_add_u64 v[16:17], v[116:117], 2, s[2:3]
	v_rcp_f32_e32 v0, v0
	v_rcp_f32_e32 v1, v1
	v_add_f32_e32 v2, 1.0, v2
	v_add_f32_e32 v3, 1.0, v3
	global_store_dwordx4 v[16:17], v[8:11], off offset:16
	v_rcp_f32_e32 v2, v2
	v_rcp_f32_e32 v3, v3
	v_lshlrev_b32_e32 v8, 16, v64
	v_and_b32_e32 v9, 0xffff0000, v64
	v_lshlrev_b32_e32 v10, 16, v68
	v_and_b32_e32 v11, 0xffff0000, v68
	v_pk_fma_f32 v[4:5], v[4:5], v[10:11], v[8:9]
	v_lshlrev_b32_e32 v8, 16, v65
	v_and_b32_e32 v9, 0xffff0000, v65
	v_lshlrev_b32_e32 v10, 16, v69
	v_and_b32_e32 v11, 0xffff0000, v69
	v_pk_fma_f32 v[6:7], v[6:7], v[10:11], v[8:9]
	v_lshlrev_b32_e32 v8, 16, v66
	v_and_b32_e32 v9, 0xffff0000, v66
	v_lshlrev_b32_e32 v10, 16, v70
	v_and_b32_e32 v11, 0xffff0000, v70
	v_pk_fma_f32 v[0:1], v[0:1], v[10:11], v[8:9]
	v_lshlrev_b32_e32 v8, 16, v67
	v_and_b32_e32 v9, 0xffff0000, v67
	v_lshlrev_b32_e32 v10, 16, v71
	v_and_b32_e32 v11, 0xffff0000, v71
	s_andn2_b64 vcc, exec, s[4:5]
	s_mov_b64 s[4:5], -1
	global_store_dwordx4 v[16:17], v[12:15], off
	v_pk_fma_f32 v[2:3], v[2:3], v[10:11], v[8:9]
	global_store_dwordx4 v[16:17], v[4:7], off offset:128
	global_store_dwordx4 v[16:17], v[0:3], off offset:144
	s_cbranch_vccnz .LBB0_803
	s_and_b64 vcc, exec, s[0:1]
	s_cbranch_vccnz .LBB0_802
	s_barrier
	s_branch .LBB0_802
